# added attention O-store widening via permlane32_swap to dwordx4, PV4-6 LDS read pipelining, P9b fix-up loads hoisted
# baseline (speedup 1.0000x reference)
; #define LAS __attribute__((address_space(3)))
; #define GAS __attribute__((address_space(1)))
; __device__ __forceinline__ unsigned cvt_pk_bf16(float lo, float hi) { unsigned r; asm volatile("v_cvt_pk_bf16_f32 %0, %1, %2" : "=v"(r) : "v"(lo), "v"(hi)); return r; }
; __device__ __forceinline__ void attn_phase(unsigned char* ws, int l, LAS unsigned char* lds, int G, int bid) {
;     ...
;         { float M = qmax[0];
; #pragma unroll
;           for (int qi = 1; qi < NQ; ++qi) M = fmaxf(M, qmax[qi]);
;           float tot = 0.f;
; #pragma unroll
;           for (int qi = 0; qi < NQ; ++qi) { fq_[qi] = __builtin_amdgcn_exp2f((qmax[qi] - M) * 1.44269504089f); tot += fq_[qi] * qsum[qi]; }
;           rinv = 1.0f / tot;
; #pragma unroll
;           for (int qi = 0; qi < NQ; ++qi) fq_[qi] *= rinv; }
;     ...
;         if (active) {
; #pragma unroll
;             for (int dt = 0; dt < 8; ++dt) {
;                 f32x16 acc[NQ];
; #pragma unroll
;                 for (int qi = 0; qi < NQ; ++qi)
; #pragma unroll
;                     for (int e = 0; e < 16; ++e) acc[qi][e] = 0.f;
; #pragma unroll
;                 for (int mi = 0; mi < 16 / NQ; ++mi)
; #pragma unroll
;                     for (int qi = 0; qi < NQ; ++qi) {
;                         const int ms = qi * (16 / NQ) + mi;
;                         const LAS unsigned char* vp = lds + (32 * dt + r32) * VST + (16 * ms + 4 * hh) * 2;
;                         const u32x2 lo = *(const LAS u32x2*)vp, hi = *(const LAS u32x2*)(vp + 16);
;                         const u32x4 w = (u32x4){lo.x, lo.y, hi.x, hi.y};
;                         acc[qi] = __builtin_amdgcn_mfma_f32_32x32x16_bf16(__builtin_bit_cast(bf16x8, w), pf[ms], acc[qi], 0, 0, 0);
;                     }
; #pragma unroll
;                 for (int g4 = 0; g4 < 4; ++g4) {
;                     float o4[4];
; #pragma unroll
;                     for (int e = 0; e < 4; ++e) { float v = 0.f;
; #pragma unroll
;                         for (int qi = 0; qi < NQ; ++qi) v = fmaf(acc[qi][4 * g4 + e], fq_[qi], v);
;                         o4[e] = v; }
;                     u32x2 w; w.x = cvt_pk_bf16(o4[0], o4[1]); w.y = cvt_pk_bf16(o4[2], o4[3]);
;                     *(GAS u32x2*)(O + (size_t)qrow * D + h * 256 + 32 * dt + 8 * g4 + 4 * hh) = w;
;                 }
;                 __builtin_amdgcn_sched_barrier(0);
.LBB0_888:
	v_max_f32_e32 v2, v248, v248
	v_max_f32_e32 v3, v254, v254
	v_max_f32_e32 v2, v3, v2
	v_max3_f32 v5, v2, v249, v32
	v_sub_f32_e32 v2, v254, v5
	v_sub_f32_e32 v3, v248, v5
	v_sub_f32_e32 v4, v249, v5
	v_sub_f32_e32 v5, v32, v5
	v_mul_f32_e32 v2, 0x3fb8aa3b, v2
	v_mul_f32_e32 v3, 0x3fb8aa3b, v3
	v_mul_f32_e32 v4, 0x3fb8aa3b, v4
	v_mul_f32_e32 v5, 0x3fb8aa3b, v5
	v_exp_f32_e32 v2, v2
	v_exp_f32_e32 v3, v3
	v_exp_f32_e32 v4, v4
	v_exp_f32_e32 v5, v5
	s_and_b64 vcc, exec, s[0:1]
	s_cbranch_vccnz .LBB0_868
	v_fma_f32 v6, v219, v2, 0
	v_fmac_f32_e32 v6, v218, v3
	v_fmac_f32_e32 v6, v1, v4
	v_fmac_f32_e32 v6, v0, v5
	v_div_scale_f32 v0, s[0:1], v6, v6, 1.0
	v_rcp_f32_e32 v1, v0
	s_lshl_b32 s62, s62, 1
	v_lshlrev_b32_e32 v64, 3, v251
	v_fma_f32 v7, -v0, v1, 1.0
	v_fmac_f32_e32 v1, v7, v1
	v_div_scale_f32 v7, vcc, 1.0, v6, 1.0
	v_mul_f32_e32 v8, v7, v1
	v_fma_f32 v9, -v0, v8, v7
	v_fmac_f32_e32 v8, v9, v1
	v_fma_f32 v0, -v0, v8, v7
	v_div_fmas_f32 v0, v0, v1, v8
	v_div_fixup_f32 v0, v0, v6, 1.0
	v_mul_f32_e32 v219, v2, v0
	v_mul_f32_e32 v218, v3, v0
	v_mul_f32_e32 v217, v4, v0
	v_mul_f32_e32 v216, v5, v0
	v_lshlrev_b64 v[0:1], 11, v[214:215]
	v_lshl_add_u64 v[0:1], s[52:53], 0, v[0:1]
	v_lshl_add_u64 v[0:1], v[0:1], 0, s[62:63]
	v_lshl_add_u64 v[214:215], v[0:1], 0, v[64:65]
	v_lshl_add_u64 v[236:237], v[214:215], 0, v[64:65]
	v_mul_u32_u24_e32 v0, 0x208, v196
	v_add3_u32 v64, 0, v64, v0
	ds_read2_b64 v[0:3], v64 offset1:2
	ds_read2_b64 v[220:223], v64 offset0:4 offset1:6
	s_waitcnt lgkmcnt(1)
	v_mfma_f32_32x32x16_bf16 v[0:15], v[0:3], v[82:85], 0
	ds_read2_b64 v[16:19], v64 offset0:16 offset1:18
	ds_read2_b64 v[32:35], v64 offset0:32 offset1:34
	ds_read2_b64 v[48:51], v64 offset0:48 offset1:50
	s_waitcnt lgkmcnt(3)
	v_mfma_f32_32x32x16_bf16 v[0:15], v[220:223], v[78:81], v[0:15]
	ds_read2_b64 v[220:223], v64 offset0:20 offset1:22
	s_waitcnt lgkmcnt(3)
	v_mfma_f32_32x32x16_bf16 v[16:31], v[16:19], v[98:101], 0
	s_waitcnt lgkmcnt(0)
	v_mfma_f32_32x32x16_bf16 v[16:31], v[220:223], v[90:93], v[16:31]
	ds_read2_b64 v[220:223], v64 offset0:36 offset1:38
	ds_read2_b64 v[224:227], v64 offset0:52 offset1:54
	ds_read2_b64 v[228:231], v64 offset0:8 offset1:10
	v_mfma_f32_32x32x16_bf16 v[32:47], v[32:35], v[114:117], 0
	s_waitcnt lgkmcnt(2)
	v_mfma_f32_32x32x16_bf16 v[32:47], v[220:223], v[110:113], v[32:47]
	ds_read2_b64 v[220:223], v64 offset0:24 offset1:26
	v_mfma_f32_32x32x16_bf16 v[48:63], v[48:51], v[182:185], 0
	s_waitcnt lgkmcnt(2)
	v_mfma_f32_32x32x16_bf16 v[48:63], v[224:227], v[146:149], v[48:63]
	ds_read2_b64 v[224:227], v64 offset0:40 offset1:42
	s_waitcnt lgkmcnt(2)
	v_mfma_f32_32x32x16_bf16 v[0:15], v[228:231], v[74:77], v[0:15]
	ds_read2_b64 v[228:231], v64 offset0:56 offset1:58
	s_waitcnt lgkmcnt(2)
	v_mfma_f32_32x32x16_bf16 v[16:31], v[220:223], v[94:97], v[16:31]
	ds_read2_b64 v[220:223], v64 offset0:12 offset1:14
	s_waitcnt lgkmcnt(2)
	v_mfma_f32_32x32x16_bf16 v[32:47], v[224:227], v[106:109], v[32:47]
	ds_read2_b64 v[224:227], v64 offset0:28 offset1:30
	s_waitcnt lgkmcnt(2)
	v_mfma_f32_32x32x16_bf16 v[48:63], v[228:231], v[154:157], v[48:63]
	ds_read2_b64 v[228:231], v64 offset0:44 offset1:46
	s_waitcnt lgkmcnt(2)
	v_mfma_f32_32x32x16_bf16 v[0:15], v[220:223], v[70:73], v[0:15]
	ds_read2_b64 v[220:223], v64 offset0:60 offset1:62
	s_waitcnt lgkmcnt(2)
	v_mfma_f32_32x32x16_bf16 v[16:31], v[224:227], v[86:89], v[16:31]
	s_nop 0
	s_nop 7
	v_fma_f32 v0, v0, v219, 0
	v_fma_f32 v1, v1, v219, 0
	v_fma_f32 v2, v2, v219, 0
	v_fma_f32 v3, v3, v219, 0
	v_fmac_f32_e32 v0, v16, v218
	s_waitcnt lgkmcnt(1)
	v_mfma_f32_32x32x16_bf16 v[32:47], v[228:231], v[102:105], v[32:47]
	s_nop 0
	v_fmac_f32_e32 v1, v17, v218
	v_fmac_f32_e32 v2, v18, v218
	v_fmac_f32_e32 v3, v19, v218
	s_nop 7
	v_fmac_f32_e32 v0, v32, v217
	s_waitcnt lgkmcnt(0)
	v_mfma_f32_32x32x16_bf16 v[48:63], v[220:223], v[130:133], v[48:63]
	v_fmac_f32_e32 v1, v33, v217
	v_fmac_f32_e32 v2, v34, v217
	v_fmac_f32_e32 v3, v35, v217
	s_nop 8
	v_fmac_f32_e32 v0, v48, v216
	v_fmac_f32_e32 v1, v49, v216
	v_fmac_f32_e32 v2, v50, v216
	v_fmac_f32_e32 v3, v51, v216
	v_cvt_pk_bf16_f32 v0, v0, v1
	v_cvt_pk_bf16_f32 v1, v2, v3
	s_nop 0
	v_fma_f32 v232, v4, v219, 0
	v_fma_f32 v233, v5, v219, 0
	v_fmac_f32_e32 v232, v20, v218
	v_fmac_f32_e32 v233, v21, v218
	v_fma_f32 v234, v6, v219, 0
	v_fma_f32 v235, v7, v219, 0
	v_fmac_f32_e32 v232, v36, v217
	v_fmac_f32_e32 v233, v37, v217
	v_fmac_f32_e32 v234, v22, v218
	v_fmac_f32_e32 v235, v23, v218
	v_fmac_f32_e32 v232, v52, v216
	v_fmac_f32_e32 v233, v53, v216
	v_fmac_f32_e32 v234, v38, v217
	v_fmac_f32_e32 v235, v39, v217
	v_fmac_f32_e32 v234, v54, v216
	v_fmac_f32_e32 v235, v55, v216
	v_cvt_pk_bf16_f32 v2, v232, v233
	v_cvt_pk_bf16_f32 v3, v234, v235
	s_nop 1
	v_permlane32_swap_b32_e32 v0, v2
	v_permlane32_swap_b32_e32 v1, v3
	global_store_dwordx4 v[236:237], v[0:3], off
	s_nop 1
	v_fma_f32 v0, v8, v219, 0
	v_fma_f32 v1, v9, v219, 0
	v_fmac_f32_e32 v0, v24, v218
	v_fmac_f32_e32 v1, v25, v218
	v_fma_f32 v2, v10, v219, 0
	v_fma_f32 v3, v11, v219, 0
	v_fmac_f32_e32 v0, v40, v217
	v_fmac_f32_e32 v1, v41, v217
	v_fmac_f32_e32 v2, v26, v218
	v_fmac_f32_e32 v3, v27, v218
	v_fmac_f32_e32 v0, v56, v216
	v_fmac_f32_e32 v1, v57, v216
	v_fmac_f32_e32 v2, v42, v217
	v_fmac_f32_e32 v3, v43, v217
	v_fmac_f32_e32 v2, v58, v216
	v_fmac_f32_e32 v3, v59, v216
	v_cvt_pk_bf16_f32 v0, v0, v1
	v_cvt_pk_bf16_f32 v1, v2, v3
	s_nop 0
	v_fma_f32 v232, v12, v219, 0
	v_fma_f32 v233, v13, v219, 0
	v_fmac_f32_e32 v232, v28, v218
	v_fmac_f32_e32 v233, v29, v218
	v_fma_f32 v234, v14, v219, 0
	v_fma_f32 v235, v15, v219, 0
	v_fmac_f32_e32 v232, v44, v217
	v_fmac_f32_e32 v233, v45, v217
	v_fmac_f32_e32 v234, v30, v218
	v_fmac_f32_e32 v235, v31, v218
	v_fmac_f32_e32 v232, v60, v216
	v_fmac_f32_e32 v233, v61, v216
	v_fmac_f32_e32 v234, v46, v217
	v_fmac_f32_e32 v235, v47, v217
	v_fmac_f32_e32 v234, v62, v216
	v_fmac_f32_e32 v235, v63, v216
	v_cvt_pk_bf16_f32 v2, v232, v233
	v_cvt_pk_bf16_f32 v3, v234, v235
	s_nop 1
	v_permlane32_swap_b32_e32 v0, v2
	v_permlane32_swap_b32_e32 v1, v3
	global_store_dwordx4 v[236:237], v[0:3], off offset:32
	s_nop 1
	v_add_u32_e32 v196, 0x4000, v64
	ds_read2_b64 v[0:3], v196 offset0:32 offset1:34
	ds_read2_b64 v[220:223], v196 offset0:36 offset1:38
	ds_read2_b64 v[16:19], v196 offset0:48 offset1:50
	ds_read2_b64 v[32:35], v196 offset0:64 offset1:66
	ds_read2_b64 v[48:51], v196 offset0:80 offset1:82
	s_waitcnt lgkmcnt(4)
; #define LAS __attribute__((address_space(3)))
; #define GAS __attribute__((address_space(1)))
; __device__ __forceinline__ unsigned cvt_pk_bf16(float lo, float hi) { unsigned r; asm volatile("v_cvt_pk_bf16_f32 %0, %1, %2" : "=v"(r) : "v"(lo), "v"(hi)); return r; }
; __device__ __forceinline__ void attn_phase(unsigned char* ws, int l, LAS unsigned char* lds, int G, int bid) {
;     ...
;                 for (int mi = 0; mi < 16 / NQ; ++mi)
; #pragma unroll
;                     for (int qi = 0; qi < NQ; ++qi) {
;                         const int ms = qi * (16 / NQ) + mi;
;                         const LAS unsigned char* vp = lds + (32 * dt + r32) * VST + (16 * ms + 4 * hh) * 2;
;                         const u32x2 lo = *(const LAS u32x2*)vp, hi = *(const LAS u32x2*)(vp + 16);
;                         const u32x4 w = (u32x4){lo.x, lo.y, hi.x, hi.y};
;                         acc[qi] = __builtin_amdgcn_mfma_f32_32x32x16_bf16(__builtin_bit_cast(bf16x8, w), pf[ms], acc[qi], 0, 0, 0);
;                     }
; #pragma unroll
;                 for (int g4 = 0; g4 < 4; ++g4) {
;                     float o4[4];
; #pragma unroll
;                     for (int e = 0; e < 4; ++e) { float v = 0.f;
; #pragma unroll
;                         for (int qi = 0; qi < NQ; ++qi) v = fmaf(acc[qi][4 * g4 + e], fq_[qi], v);
;                         o4[e] = v; }
;                     u32x2 w; w.x = cvt_pk_bf16(o4[0], o4[1]); w.y = cvt_pk_bf16(o4[2], o4[3]);
;                     *(GAS u32x2*)(O + (size_t)qrow * D + h * 256 + 32 * dt + 8 * g4 + 4 * hh) = w;
;                 }
	v_mfma_f32_32x32x16_bf16 v[0:15], v[0:3], v[82:85], 0
	s_waitcnt lgkmcnt(3)
	v_mfma_f32_32x32x16_bf16 v[0:15], v[220:223], v[78:81], v[0:15]
	ds_read2_b64 v[220:223], v196 offset0:52 offset1:54
	s_waitcnt lgkmcnt(3)
	v_mfma_f32_32x32x16_bf16 v[16:31], v[16:19], v[98:101], 0
	s_waitcnt lgkmcnt(0)
	v_mfma_f32_32x32x16_bf16 v[16:31], v[220:223], v[90:93], v[16:31]
	ds_read2_b64 v[220:223], v196 offset0:68 offset1:70
	ds_read2_b64 v[224:227], v196 offset0:84 offset1:86
	ds_read2_b64 v[228:231], v196 offset0:40 offset1:42
	v_mfma_f32_32x32x16_bf16 v[32:47], v[32:35], v[114:117], 0
	s_waitcnt lgkmcnt(2)
	v_mfma_f32_32x32x16_bf16 v[32:47], v[220:223], v[110:113], v[32:47]
	ds_read2_b64 v[220:223], v196 offset0:56 offset1:58
	v_mfma_f32_32x32x16_bf16 v[48:63], v[48:51], v[182:185], 0
	s_waitcnt lgkmcnt(2)
	v_mfma_f32_32x32x16_bf16 v[48:63], v[224:227], v[146:149], v[48:63]
	ds_read2_b64 v[224:227], v196 offset0:72 offset1:74
	s_waitcnt lgkmcnt(2)
	v_mfma_f32_32x32x16_bf16 v[0:15], v[228:231], v[74:77], v[0:15]
	ds_read2_b64 v[228:231], v196 offset0:88 offset1:90
	s_waitcnt lgkmcnt(2)
	v_mfma_f32_32x32x16_bf16 v[16:31], v[220:223], v[94:97], v[16:31]
	ds_read2_b64 v[220:223], v196 offset0:44 offset1:46
	s_waitcnt lgkmcnt(2)
	v_mfma_f32_32x32x16_bf16 v[32:47], v[224:227], v[106:109], v[32:47]
	ds_read2_b64 v[224:227], v196 offset0:60 offset1:62
	s_waitcnt lgkmcnt(2)
	v_mfma_f32_32x32x16_bf16 v[48:63], v[228:231], v[154:157], v[48:63]
	ds_read2_b64 v[228:231], v196 offset0:76 offset1:78
	s_waitcnt lgkmcnt(2)
	v_mfma_f32_32x32x16_bf16 v[0:15], v[220:223], v[70:73], v[0:15]
	ds_read2_b64 v[220:223], v196 offset0:92 offset1:94
	s_waitcnt lgkmcnt(2)
	v_mfma_f32_32x32x16_bf16 v[16:31], v[224:227], v[86:89], v[16:31]
	s_nop 0
	s_nop 7
	v_fma_f32 v0, v0, v219, 0
	v_fma_f32 v1, v1, v219, 0
	v_fma_f32 v2, v2, v219, 0
	v_fma_f32 v3, v3, v219, 0
	v_fmac_f32_e32 v0, v16, v218
	s_waitcnt lgkmcnt(1)
	v_mfma_f32_32x32x16_bf16 v[32:47], v[228:231], v[102:105], v[32:47]
	s_nop 0
	v_fmac_f32_e32 v1, v17, v218
	v_fmac_f32_e32 v2, v18, v218
	v_fmac_f32_e32 v3, v19, v218
	s_nop 7
	v_fmac_f32_e32 v0, v32, v217
	s_waitcnt lgkmcnt(0)
	v_mfma_f32_32x32x16_bf16 v[48:63], v[220:223], v[130:133], v[48:63]
	v_fmac_f32_e32 v1, v33, v217
	v_fmac_f32_e32 v2, v34, v217
	v_fmac_f32_e32 v3, v35, v217
	s_nop 8
	v_fmac_f32_e32 v0, v48, v216
	v_fmac_f32_e32 v1, v49, v216
	v_fmac_f32_e32 v2, v50, v216
	v_fmac_f32_e32 v3, v51, v216
	v_cvt_pk_bf16_f32 v0, v0, v1
	v_cvt_pk_bf16_f32 v1, v2, v3
	s_nop 0
	v_fma_f32 v232, v4, v219, 0
	v_fma_f32 v233, v5, v219, 0
	v_fmac_f32_e32 v232, v20, v218
	v_fmac_f32_e32 v233, v21, v218
	v_fma_f32 v234, v6, v219, 0
	v_fma_f32 v235, v7, v219, 0
	v_fmac_f32_e32 v232, v36, v217
	v_fmac_f32_e32 v233, v37, v217
	v_fmac_f32_e32 v234, v22, v218
	v_fmac_f32_e32 v235, v23, v218
	v_fmac_f32_e32 v232, v52, v216
	v_fmac_f32_e32 v233, v53, v216
	v_fmac_f32_e32 v234, v38, v217
	v_fmac_f32_e32 v235, v39, v217
	v_fmac_f32_e32 v234, v54, v216
	v_fmac_f32_e32 v235, v55, v216
	v_cvt_pk_bf16_f32 v2, v232, v233
	v_cvt_pk_bf16_f32 v3, v234, v235
	s_nop 1
	v_permlane32_swap_b32_e32 v0, v2
	v_permlane32_swap_b32_e32 v1, v3
	global_store_dwordx4 v[236:237], v[0:3], off offset:64
	s_nop 1
	v_fma_f32 v0, v8, v219, 0
	v_fma_f32 v1, v9, v219, 0
	v_fmac_f32_e32 v0, v24, v218
	v_fmac_f32_e32 v1, v25, v218
	v_fma_f32 v2, v10, v219, 0
	v_fma_f32 v3, v11, v219, 0
	v_fmac_f32_e32 v0, v40, v217
	v_fmac_f32_e32 v1, v41, v217
	v_fmac_f32_e32 v2, v26, v218
	v_fmac_f32_e32 v3, v27, v218
	v_fmac_f32_e32 v0, v56, v216
	v_fmac_f32_e32 v1, v57, v216
	v_fmac_f32_e32 v2, v42, v217
	v_fmac_f32_e32 v3, v43, v217
	v_fmac_f32_e32 v2, v58, v216
	v_fmac_f32_e32 v3, v59, v216
	v_cvt_pk_bf16_f32 v0, v0, v1
	v_cvt_pk_bf16_f32 v1, v2, v3
	s_nop 0
	v_fma_f32 v232, v12, v219, 0
	v_fma_f32 v233, v13, v219, 0
	v_fmac_f32_e32 v232, v28, v218
	v_fmac_f32_e32 v233, v29, v218
	v_fma_f32 v234, v14, v219, 0
	v_fma_f32 v235, v15, v219, 0
	v_fmac_f32_e32 v232, v44, v217
	v_fmac_f32_e32 v233, v45, v217
	v_fmac_f32_e32 v234, v30, v218
	v_fmac_f32_e32 v235, v31, v218
	v_fmac_f32_e32 v232, v60, v216
	v_fmac_f32_e32 v233, v61, v216
	v_fmac_f32_e32 v234, v46, v217
	v_fmac_f32_e32 v235, v47, v217
	v_fmac_f32_e32 v234, v62, v216
	v_fmac_f32_e32 v235, v63, v216
	v_cvt_pk_bf16_f32 v2, v232, v233
	v_cvt_pk_bf16_f32 v3, v234, v235
	s_nop 1
	v_permlane32_swap_b32_e32 v0, v2
	v_permlane32_swap_b32_e32 v1, v3
	global_store_dwordx4 v[236:237], v[0:3], off offset:96
	s_nop 1
	v_add_u32_e32 v196, 0x8000, v64
	ds_read2_b64 v[0:3], v196 offset0:64 offset1:66
	ds_read2_b64 v[220:223], v196 offset0:68 offset1:70
	ds_read2_b64 v[16:19], v196 offset0:80 offset1:82
	ds_read2_b64 v[32:35], v196 offset0:96 offset1:98
	ds_read2_b64 v[48:51], v196 offset0:112 offset1:114
	s_waitcnt lgkmcnt(4)
	v_mfma_f32_32x32x16_bf16 v[0:15], v[0:3], v[82:85], 0
	s_waitcnt lgkmcnt(3)
	v_mfma_f32_32x32x16_bf16 v[0:15], v[220:223], v[78:81], v[0:15]
	ds_read2_b64 v[220:223], v196 offset0:84 offset1:86
	s_waitcnt lgkmcnt(3)
	v_mfma_f32_32x32x16_bf16 v[16:31], v[16:19], v[98:101], 0
	s_waitcnt lgkmcnt(0)
	v_mfma_f32_32x32x16_bf16 v[16:31], v[220:223], v[90:93], v[16:31]
	ds_read2_b64 v[220:223], v196 offset0:100 offset1:102
	ds_read2_b64 v[224:227], v196 offset0:116 offset1:118
	ds_read2_b64 v[228:231], v196 offset0:72 offset1:74
	v_mfma_f32_32x32x16_bf16 v[32:47], v[32:35], v[114:117], 0
	s_waitcnt lgkmcnt(2)
	v_mfma_f32_32x32x16_bf16 v[32:47], v[220:223], v[110:113], v[32:47]
	ds_read2_b64 v[220:223], v196 offset0:88 offset1:90
	v_mfma_f32_32x32x16_bf16 v[48:63], v[48:51], v[182:185], 0
	s_waitcnt lgkmcnt(2)
; #define LAS __attribute__((address_space(3)))
; #define GAS __attribute__((address_space(1)))
; __device__ __forceinline__ unsigned cvt_pk_bf16(float lo, float hi) { unsigned r; asm volatile("v_cvt_pk_bf16_f32 %0, %1, %2" : "=v"(r) : "v"(lo), "v"(hi)); return r; }
; __device__ __forceinline__ void attn_phase(unsigned char* ws, int l, LAS unsigned char* lds, int G, int bid) {
;     ...
;                 for (int mi = 0; mi < 16 / NQ; ++mi)
; #pragma unroll
;                     for (int qi = 0; qi < NQ; ++qi) {
;                         const int ms = qi * (16 / NQ) + mi;
;                         const LAS unsigned char* vp = lds + (32 * dt + r32) * VST + (16 * ms + 4 * hh) * 2;
;                         const u32x2 lo = *(const LAS u32x2*)vp, hi = *(const LAS u32x2*)(vp + 16);
;                         const u32x4 w = (u32x4){lo.x, lo.y, hi.x, hi.y};
;                         acc[qi] = __builtin_amdgcn_mfma_f32_32x32x16_bf16(__builtin_bit_cast(bf16x8, w), pf[ms], acc[qi], 0, 0, 0);
;                     }
; #pragma unroll
;                 for (int g4 = 0; g4 < 4; ++g4) {
;                     float o4[4];
; #pragma unroll
;                     for (int e = 0; e < 4; ++e) { float v = 0.f;
; #pragma unroll
;                         for (int qi = 0; qi < NQ; ++qi) v = fmaf(acc[qi][4 * g4 + e], fq_[qi], v);
;                         o4[e] = v; }
;                     u32x2 w; w.x = cvt_pk_bf16(o4[0], o4[1]); w.y = cvt_pk_bf16(o4[2], o4[3]);
;                     *(GAS u32x2*)(O + (size_t)qrow * D + h * 256 + 32 * dt + 8 * g4 + 4 * hh) = w;
;                 }
	v_mfma_f32_32x32x16_bf16 v[48:63], v[224:227], v[146:149], v[48:63]
	ds_read2_b64 v[224:227], v196 offset0:104 offset1:106
	s_waitcnt lgkmcnt(2)
	v_mfma_f32_32x32x16_bf16 v[0:15], v[228:231], v[74:77], v[0:15]
	ds_read2_b64 v[228:231], v196 offset0:120 offset1:122
	s_waitcnt lgkmcnt(2)
	v_mfma_f32_32x32x16_bf16 v[16:31], v[220:223], v[94:97], v[16:31]
	ds_read2_b64 v[220:223], v196 offset0:76 offset1:78
	s_waitcnt lgkmcnt(2)
	v_mfma_f32_32x32x16_bf16 v[32:47], v[224:227], v[106:109], v[32:47]
	ds_read2_b64 v[224:227], v196 offset0:92 offset1:94
	s_waitcnt lgkmcnt(2)
	v_mfma_f32_32x32x16_bf16 v[48:63], v[228:231], v[154:157], v[48:63]
	ds_read2_b64 v[228:231], v196 offset0:108 offset1:110
	s_waitcnt lgkmcnt(2)
	v_mfma_f32_32x32x16_bf16 v[0:15], v[220:223], v[70:73], v[0:15]
	ds_read2_b64 v[220:223], v196 offset0:124 offset1:126
	s_waitcnt lgkmcnt(2)
	v_mfma_f32_32x32x16_bf16 v[16:31], v[224:227], v[86:89], v[16:31]
	s_nop 0
	s_nop 7
	v_fma_f32 v0, v0, v219, 0
	v_fma_f32 v1, v1, v219, 0
	v_fma_f32 v2, v2, v219, 0
	v_fma_f32 v3, v3, v219, 0
	v_fmac_f32_e32 v0, v16, v218
	s_waitcnt lgkmcnt(1)
	v_mfma_f32_32x32x16_bf16 v[32:47], v[228:231], v[102:105], v[32:47]
	s_nop 0
	v_fmac_f32_e32 v1, v17, v218
	v_fmac_f32_e32 v2, v18, v218
	v_fmac_f32_e32 v3, v19, v218
	s_nop 7
	v_fmac_f32_e32 v0, v32, v217
	s_waitcnt lgkmcnt(0)
	v_mfma_f32_32x32x16_bf16 v[48:63], v[220:223], v[130:133], v[48:63]
	v_fmac_f32_e32 v1, v33, v217
	v_fmac_f32_e32 v2, v34, v217
	v_fmac_f32_e32 v3, v35, v217
	s_nop 8
	v_fmac_f32_e32 v0, v48, v216
	v_fmac_f32_e32 v1, v49, v216
	v_fmac_f32_e32 v2, v50, v216
	v_fmac_f32_e32 v3, v51, v216
	v_cvt_pk_bf16_f32 v0, v0, v1
	v_cvt_pk_bf16_f32 v1, v2, v3
	s_nop 0
	v_fma_f32 v232, v4, v219, 0
	v_fma_f32 v233, v5, v219, 0
	v_fmac_f32_e32 v232, v20, v218
	v_fmac_f32_e32 v233, v21, v218
	v_fma_f32 v234, v6, v219, 0
	v_fma_f32 v235, v7, v219, 0
	v_fmac_f32_e32 v232, v36, v217
	v_fmac_f32_e32 v233, v37, v217
	v_fmac_f32_e32 v234, v22, v218
	v_fmac_f32_e32 v235, v23, v218
	v_fmac_f32_e32 v232, v52, v216
	v_fmac_f32_e32 v233, v53, v216
	v_fmac_f32_e32 v234, v38, v217
	v_fmac_f32_e32 v235, v39, v217
	v_fmac_f32_e32 v234, v54, v216
	v_fmac_f32_e32 v235, v55, v216
	v_cvt_pk_bf16_f32 v2, v232, v233
	v_cvt_pk_bf16_f32 v3, v234, v235
	s_nop 1
	v_permlane32_swap_b32_e32 v0, v2
	v_permlane32_swap_b32_e32 v1, v3
	global_store_dwordx4 v[236:237], v[0:3], off offset:128
	s_nop 1
	v_fma_f32 v0, v8, v219, 0
	v_fma_f32 v1, v9, v219, 0
	v_fmac_f32_e32 v0, v24, v218
	v_fmac_f32_e32 v1, v25, v218
	v_fma_f32 v2, v10, v219, 0
	v_fma_f32 v3, v11, v219, 0
	v_fmac_f32_e32 v0, v40, v217
	v_fmac_f32_e32 v1, v41, v217
	v_fmac_f32_e32 v2, v26, v218
	v_fmac_f32_e32 v3, v27, v218
	v_fmac_f32_e32 v0, v56, v216
	v_fmac_f32_e32 v1, v57, v216
	v_fmac_f32_e32 v2, v42, v217
	v_fmac_f32_e32 v3, v43, v217
	v_fmac_f32_e32 v2, v58, v216
	v_fmac_f32_e32 v3, v59, v216
	v_cvt_pk_bf16_f32 v0, v0, v1
	v_cvt_pk_bf16_f32 v1, v2, v3
	s_nop 0
	v_fma_f32 v232, v12, v219, 0
	v_fma_f32 v233, v13, v219, 0
	v_fmac_f32_e32 v232, v28, v218
	v_fmac_f32_e32 v233, v29, v218
	v_fma_f32 v234, v14, v219, 0
	v_fma_f32 v235, v15, v219, 0
	v_fmac_f32_e32 v232, v44, v217
	v_fmac_f32_e32 v233, v45, v217
	v_fmac_f32_e32 v234, v30, v218
	v_fmac_f32_e32 v235, v31, v218
	v_fmac_f32_e32 v232, v60, v216
	v_fmac_f32_e32 v233, v61, v216
	v_fmac_f32_e32 v234, v46, v217
	v_fmac_f32_e32 v235, v47, v217
	v_fmac_f32_e32 v234, v62, v216
	v_fmac_f32_e32 v235, v63, v216
	v_cvt_pk_bf16_f32 v2, v232, v233
	v_cvt_pk_bf16_f32 v3, v234, v235
	s_nop 1
	v_permlane32_swap_b32_e32 v0, v2
	v_permlane32_swap_b32_e32 v1, v3
	global_store_dwordx4 v[236:237], v[0:3], off offset:160
	s_nop 1
	v_add_u32_e32 v196, 0xc000, v64
	ds_read2_b64 v[0:3], v196 offset0:96 offset1:98
	ds_read2_b64 v[220:223], v196 offset0:100 offset1:102
	ds_read2_b64 v[16:19], v196 offset0:112 offset1:114
	ds_read2_b64 v[32:35], v196 offset0:128 offset1:130
	ds_read2_b64 v[48:51], v196 offset0:144 offset1:146
	s_waitcnt lgkmcnt(4)
	v_mfma_f32_32x32x16_bf16 v[0:15], v[0:3], v[82:85], 0
	s_waitcnt lgkmcnt(3)
	v_mfma_f32_32x32x16_bf16 v[0:15], v[220:223], v[78:81], v[0:15]
	ds_read2_b64 v[220:223], v196 offset0:116 offset1:118
	s_waitcnt lgkmcnt(3)
	v_mfma_f32_32x32x16_bf16 v[16:31], v[16:19], v[98:101], 0
	s_waitcnt lgkmcnt(0)
	v_mfma_f32_32x32x16_bf16 v[16:31], v[220:223], v[90:93], v[16:31]
	ds_read2_b64 v[220:223], v196 offset0:132 offset1:134
	ds_read2_b64 v[224:227], v196 offset0:148 offset1:150
	ds_read2_b64 v[228:231], v196 offset0:104 offset1:106
	v_mfma_f32_32x32x16_bf16 v[32:47], v[32:35], v[114:117], 0
	s_waitcnt lgkmcnt(2)
	v_mfma_f32_32x32x16_bf16 v[32:47], v[220:223], v[110:113], v[32:47]
	ds_read2_b64 v[220:223], v196 offset0:120 offset1:122
	v_mfma_f32_32x32x16_bf16 v[48:63], v[48:51], v[182:185], 0
	s_waitcnt lgkmcnt(2)
	v_mfma_f32_32x32x16_bf16 v[48:63], v[224:227], v[146:149], v[48:63]
	ds_read2_b64 v[224:227], v196 offset0:136 offset1:138
	s_waitcnt lgkmcnt(2)
	v_mfma_f32_32x32x16_bf16 v[0:15], v[228:231], v[74:77], v[0:15]
	ds_read2_b64 v[228:231], v196 offset0:152 offset1:154
	s_waitcnt lgkmcnt(2)
	v_mfma_f32_32x32x16_bf16 v[16:31], v[220:223], v[94:97], v[16:31]
	ds_read2_b64 v[220:223], v196 offset0:108 offset1:110
	s_waitcnt lgkmcnt(2)
	v_mfma_f32_32x32x16_bf16 v[32:47], v[224:227], v[106:109], v[32:47]
	ds_read2_b64 v[224:227], v196 offset0:124 offset1:126
	s_waitcnt lgkmcnt(2)
	v_mfma_f32_32x32x16_bf16 v[48:63], v[228:231], v[154:157], v[48:63]
	ds_read2_b64 v[228:231], v196 offset0:140 offset1:142
	s_waitcnt lgkmcnt(2)
	v_mfma_f32_32x32x16_bf16 v[0:15], v[220:223], v[70:73], v[0:15]
	ds_read2_b64 v[220:223], v196 offset0:156 offset1:158
	s_waitcnt lgkmcnt(2)
; #define LAS __attribute__((address_space(3)))
; #define GAS __attribute__((address_space(1)))
; __device__ __forceinline__ unsigned cvt_pk_bf16(float lo, float hi) { unsigned r; asm volatile("v_cvt_pk_bf16_f32 %0, %1, %2" : "=v"(r) : "v"(lo), "v"(hi)); return r; }
; __device__ __forceinline__ void attn_phase(unsigned char* ws, int l, LAS unsigned char* lds, int G, int bid) {
;     ...
;                 for (int mi = 0; mi < 16 / NQ; ++mi)
; #pragma unroll
;                     for (int qi = 0; qi < NQ; ++qi) {
;                         const int ms = qi * (16 / NQ) + mi;
;                         const LAS unsigned char* vp = lds + (32 * dt + r32) * VST + (16 * ms + 4 * hh) * 2;
;                         const u32x2 lo = *(const LAS u32x2*)vp, hi = *(const LAS u32x2*)(vp + 16);
;                         const u32x4 w = (u32x4){lo.x, lo.y, hi.x, hi.y};
;                         acc[qi] = __builtin_amdgcn_mfma_f32_32x32x16_bf16(__builtin_bit_cast(bf16x8, w), pf[ms], acc[qi], 0, 0, 0);
;                     }
; #pragma unroll
;                 for (int g4 = 0; g4 < 4; ++g4) {
;                     float o4[4];
; #pragma unroll
;                     for (int e = 0; e < 4; ++e) { float v = 0.f;
; #pragma unroll
;                         for (int qi = 0; qi < NQ; ++qi) v = fmaf(acc[qi][4 * g4 + e], fq_[qi], v);
;                         o4[e] = v; }
;                     u32x2 w; w.x = cvt_pk_bf16(o4[0], o4[1]); w.y = cvt_pk_bf16(o4[2], o4[3]);
;                     *(GAS u32x2*)(O + (size_t)qrow * D + h * 256 + 32 * dt + 8 * g4 + 4 * hh) = w;
;                 }
	v_mfma_f32_32x32x16_bf16 v[16:31], v[224:227], v[86:89], v[16:31]
	s_nop 0
	s_nop 7
	v_fma_f32 v0, v0, v219, 0
	v_fma_f32 v1, v1, v219, 0
	v_fma_f32 v2, v2, v219, 0
	v_fma_f32 v3, v3, v219, 0
	v_fmac_f32_e32 v0, v16, v218
	s_waitcnt lgkmcnt(1)
	v_mfma_f32_32x32x16_bf16 v[32:47], v[228:231], v[102:105], v[32:47]
	s_nop 0
	v_fmac_f32_e32 v1, v17, v218
	v_fmac_f32_e32 v2, v18, v218
	v_fmac_f32_e32 v3, v19, v218
	s_nop 7
	v_fmac_f32_e32 v0, v32, v217
	s_waitcnt lgkmcnt(0)
	v_mfma_f32_32x32x16_bf16 v[48:63], v[220:223], v[130:133], v[48:63]
	v_fmac_f32_e32 v1, v33, v217
	v_fmac_f32_e32 v2, v34, v217
	v_fmac_f32_e32 v3, v35, v217
	s_nop 8
	v_fmac_f32_e32 v0, v48, v216
	v_fmac_f32_e32 v1, v49, v216
	v_fmac_f32_e32 v2, v50, v216
	v_fmac_f32_e32 v3, v51, v216
	v_cvt_pk_bf16_f32 v0, v0, v1
	v_cvt_pk_bf16_f32 v1, v2, v3
	s_nop 0
	v_fma_f32 v232, v4, v219, 0
	v_fma_f32 v233, v5, v219, 0
	v_fmac_f32_e32 v232, v20, v218
	v_fmac_f32_e32 v233, v21, v218
	v_fma_f32 v234, v6, v219, 0
	v_fma_f32 v235, v7, v219, 0
	v_fmac_f32_e32 v232, v36, v217
	v_fmac_f32_e32 v233, v37, v217
	v_fmac_f32_e32 v234, v22, v218
	v_fmac_f32_e32 v235, v23, v218
	v_fmac_f32_e32 v232, v52, v216
	v_fmac_f32_e32 v233, v53, v216
	v_fmac_f32_e32 v234, v38, v217
	v_fmac_f32_e32 v235, v39, v217
	v_fmac_f32_e32 v234, v54, v216
	v_fmac_f32_e32 v235, v55, v216
	v_cvt_pk_bf16_f32 v2, v232, v233
	v_cvt_pk_bf16_f32 v3, v234, v235
	s_nop 1
	v_permlane32_swap_b32_e32 v0, v2
	v_permlane32_swap_b32_e32 v1, v3
	global_store_dwordx4 v[236:237], v[0:3], off offset:192
	s_nop 1
	v_fma_f32 v0, v8, v219, 0
	v_fma_f32 v1, v9, v219, 0
	v_fmac_f32_e32 v0, v24, v218
	v_fmac_f32_e32 v1, v25, v218
	v_fma_f32 v2, v10, v219, 0
	v_fma_f32 v3, v11, v219, 0
	v_fmac_f32_e32 v0, v40, v217
	v_fmac_f32_e32 v1, v41, v217
	v_fmac_f32_e32 v2, v26, v218
	v_fmac_f32_e32 v3, v27, v218
	v_fmac_f32_e32 v0, v56, v216
	v_fmac_f32_e32 v1, v57, v216
	v_fmac_f32_e32 v2, v42, v217
	v_fmac_f32_e32 v3, v43, v217
	v_fmac_f32_e32 v2, v58, v216
	v_fmac_f32_e32 v3, v59, v216
	v_cvt_pk_bf16_f32 v0, v0, v1
	v_cvt_pk_bf16_f32 v1, v2, v3
	s_nop 0
	v_fma_f32 v232, v12, v219, 0
	v_fma_f32 v233, v13, v219, 0
	v_fmac_f32_e32 v232, v28, v218
	v_fmac_f32_e32 v233, v29, v218
	v_fma_f32 v234, v14, v219, 0
	v_fma_f32 v235, v15, v219, 0
	v_fmac_f32_e32 v232, v44, v217
	v_fmac_f32_e32 v233, v45, v217
	v_fmac_f32_e32 v234, v30, v218
	v_fmac_f32_e32 v235, v31, v218
	v_fmac_f32_e32 v232, v60, v216
	v_fmac_f32_e32 v233, v61, v216
	v_fmac_f32_e32 v234, v46, v217
	v_fmac_f32_e32 v235, v47, v217
	v_fmac_f32_e32 v234, v62, v216
	v_fmac_f32_e32 v235, v63, v216
	v_cvt_pk_bf16_f32 v2, v232, v233
	v_cvt_pk_bf16_f32 v3, v234, v235
	s_nop 1
	v_permlane32_swap_b32_e32 v0, v2
	v_permlane32_swap_b32_e32 v1, v3
	global_store_dwordx4 v[236:237], v[0:3], off offset:224
	s_nop 1
	v_add_u32_e32 v0, 0x10400, v64
	v_add_u32_e32 v2, 0x10410, v64
	ds_read_b64 v[0:1], v0
	ds_read_b64 v[2:3], v2
	v_add_u32_e32 v196, 0x10420, v64
	ds_read_b64 v[220:221], v196
	v_add_u32_e32 v196, 0x10430, v64
	v_add_u32_e32 v16, 0x10480, v64
	v_add_u32_e32 v18, 0x10490, v64
	ds_read_b64 v[222:223], v196
	ds_read_b64 v[16:17], v16
	ds_read_b64 v[18:19], v18
	s_waitcnt lgkmcnt(4)
	v_mfma_f32_32x32x16_bf16 v[0:15], v[0:3], v[82:85], 0
	v_add_u32_e32 v196, 0x104a0, v64
	v_add_u32_e32 v32, 0x10500, v64
	v_add_u32_e32 v34, 0x10510, v64
	ds_read_b64 v[32:33], v32
	ds_read_b64 v[34:35], v34
	v_add_u32_e32 v48, 0x10580, v64
	v_add_u32_e32 v50, 0x10590, v64
	s_waitcnt lgkmcnt(4)
	v_mfma_f32_32x32x16_bf16 v[0:15], v[220:223], v[78:81], v[0:15]
	ds_read_b64 v[220:221], v196
	v_add_u32_e32 v196, 0x104b0, v64
	ds_read_b64 v[222:223], v196
	v_add_u32_e32 v196, 0x10520, v64
	ds_read_b64 v[48:49], v48
	ds_read_b64 v[50:51], v50
	s_waitcnt lgkmcnt(6)
	v_mfma_f32_32x32x16_bf16 v[16:31], v[16:19], v[98:101], 0
	s_waitcnt lgkmcnt(2)
	v_mfma_f32_32x32x16_bf16 v[16:31], v[220:223], v[90:93], v[16:31]
	v_add_u32_e32 v240, 0x10400, v64
	ds_read_b64 v[220:221], v240 offset:288
	v_add_u32_e32 v196, 0x10530, v64
	ds_read_b64 v[222:223], v240 offset:304
	ds_read_b64 v[224:225], v240 offset:416
	ds_read_b64 v[226:227], v240 offset:432
	ds_read_b64 v[228:229], v240 offset:64
	ds_read_b64 v[230:231], v240 offset:80
	v_add_u32_e32 v196, 0x105a0, v64
	v_mfma_f32_32x32x16_bf16 v[32:47], v[32:35], v[114:117], 0
	s_waitcnt lgkmcnt(4)
	v_mfma_f32_32x32x16_bf16 v[32:47], v[220:223], v[110:113], v[32:47]
	ds_read_b64 v[220:221], v240 offset:192
	v_add_u32_e32 v196, 0x105b0, v64
	ds_read_b64 v[222:223], v240 offset:208
	v_add_u32_e32 v196, 0x10440, v64
	v_mfma_f32_32x32x16_bf16 v[48:63], v[48:51], v[182:185], 0
	s_waitcnt lgkmcnt(4)
	v_mfma_f32_32x32x16_bf16 v[48:63], v[224:227], v[146:149], v[48:63]
	ds_read_b64 v[224:225], v240 offset:320
	v_add_u32_e32 v196, 0x10450, v64
	ds_read_b64 v[226:227], v240 offset:336
	v_add_u32_e32 v196, 0x104c0, v64
	s_waitcnt lgkmcnt(4)
	v_mfma_f32_32x32x16_bf16 v[0:15], v[228:231], v[74:77], v[0:15]
	ds_read_b64 v[228:229], v240 offset:448
	v_add_u32_e32 v196, 0x104d0, v64
	ds_read_b64 v[230:231], v240 offset:464
	v_add_u32_e32 v196, 0x10540, v64
	s_waitcnt lgkmcnt(4)
	v_mfma_f32_32x32x16_bf16 v[16:31], v[220:223], v[94:97], v[16:31]
	ds_read_b64 v[220:221], v240 offset:96
	v_add_u32_e32 v196, 0x10550, v64
	ds_read_b64 v[222:223], v240 offset:112
	v_add_u32_e32 v196, 0x105c0, v64
	s_waitcnt lgkmcnt(4)
	v_mfma_f32_32x32x16_bf16 v[32:47], v[224:227], v[106:109], v[32:47]
	ds_read_b64 v[224:225], v240 offset:224
	v_add_u32_e32 v196, 0x105d0, v64
	ds_read_b64 v[226:227], v240 offset:240
	v_add_u32_e32 v196, 0x10460, v64
	s_waitcnt lgkmcnt(4)
; #define LAS __attribute__((address_space(3)))
; #define GAS __attribute__((address_space(1)))
; __device__ __forceinline__ unsigned cvt_pk_bf16(float lo, float hi) { unsigned r; asm volatile("v_cvt_pk_bf16_f32 %0, %1, %2" : "=v"(r) : "v"(lo), "v"(hi)); return r; }
; __device__ __forceinline__ void attn_phase(unsigned char* ws, int l, LAS unsigned char* lds, int G, int bid) {
;     ...
;                 for (int mi = 0; mi < 16 / NQ; ++mi)
; #pragma unroll
;                     for (int qi = 0; qi < NQ; ++qi) {
;                         const int ms = qi * (16 / NQ) + mi;
;                         const LAS unsigned char* vp = lds + (32 * dt + r32) * VST + (16 * ms + 4 * hh) * 2;
;                         const u32x2 lo = *(const LAS u32x2*)vp, hi = *(const LAS u32x2*)(vp + 16);
;                         const u32x4 w = (u32x4){lo.x, lo.y, hi.x, hi.y};
;                         acc[qi] = __builtin_amdgcn_mfma_f32_32x32x16_bf16(__builtin_bit_cast(bf16x8, w), pf[ms], acc[qi], 0, 0, 0);
;                     }
; #pragma unroll
;                 for (int g4 = 0; g4 < 4; ++g4) {
;                     float o4[4];
; #pragma unroll
;                     for (int e = 0; e < 4; ++e) { float v = 0.f;
; #pragma unroll
;                         for (int qi = 0; qi < NQ; ++qi) v = fmaf(acc[qi][4 * g4 + e], fq_[qi], v);
;                         o4[e] = v; }
;                     u32x2 w; w.x = cvt_pk_bf16(o4[0], o4[1]); w.y = cvt_pk_bf16(o4[2], o4[3]);
;                     *(GAS u32x2*)(O + (size_t)qrow * D + h * 256 + 32 * dt + 8 * g4 + 4 * hh) = w;
;                 }
	v_mfma_f32_32x32x16_bf16 v[48:63], v[228:231], v[154:157], v[48:63]
	ds_read_b64 v[228:229], v240 offset:352
	v_add_u32_e32 v196, 0x10470, v64
	ds_read_b64 v[230:231], v240 offset:368
	v_add_u32_e32 v196, 0x104e0, v64
	s_waitcnt lgkmcnt(4)
	v_mfma_f32_32x32x16_bf16 v[0:15], v[220:223], v[70:73], v[0:15]
	ds_read_b64 v[220:221], v240 offset:480
	v_add_u32_e32 v196, 0x104f0, v64
	ds_read_b64 v[222:223], v240 offset:496
	v_add_u32_e32 v196, 0x10560, v64
	s_nop 7
	v_fma_f32 v0, v0, v219, 0
	s_waitcnt lgkmcnt(4)
	v_mfma_f32_32x32x16_bf16 v[16:31], v[224:227], v[86:89], v[16:31]
	s_nop 0
	v_add_u32_e32 v196, 0x10570, v64
	s_nop 0
	v_add_u32_e32 v196, 0x105e0, v64
	v_fma_f32 v1, v1, v219, 0
	v_fma_f32 v2, v2, v219, 0
	v_fma_f32 v3, v3, v219, 0
	s_waitcnt lgkmcnt(2)
	v_mfma_f32_32x32x16_bf16 v[32:47], v[228:231], v[102:105], v[32:47]
	s_nop 0
	v_add_u32_e32 v196, 0x105f0, v64
	s_nop 0
	v_fmac_f32_e32 v0, v16, v218
	v_fmac_f32_e32 v1, v17, v218
	v_fmac_f32_e32 v2, v18, v218
	v_fmac_f32_e32 v3, v19, v218
	s_waitcnt lgkmcnt(0)
	v_mfma_f32_32x32x16_bf16 v[48:63], v[220:223], v[130:133], v[48:63]
	s_nop 2
	v_fmac_f32_e32 v0, v32, v217
	v_fmac_f32_e32 v1, v33, v217
	v_fmac_f32_e32 v2, v34, v217
	v_fmac_f32_e32 v3, v35, v217
	s_nop 4
	v_fmac_f32_e32 v0, v48, v216
	v_fmac_f32_e32 v1, v49, v216
	v_fmac_f32_e32 v2, v50, v216
	v_fmac_f32_e32 v3, v51, v216
	v_cvt_pk_bf16_f32 v0, v0, v1
	v_cvt_pk_bf16_f32 v1, v2, v3
	s_nop 0
	v_fma_f32 v232, v4, v219, 0
	v_fma_f32 v233, v5, v219, 0
	v_fmac_f32_e32 v232, v20, v218
	v_fmac_f32_e32 v233, v21, v218
	v_fma_f32 v234, v6, v219, 0
	v_fma_f32 v235, v7, v219, 0
	v_fmac_f32_e32 v232, v36, v217
	v_fmac_f32_e32 v233, v37, v217
	v_fmac_f32_e32 v234, v22, v218
	v_fmac_f32_e32 v235, v23, v218
	v_fmac_f32_e32 v232, v52, v216
	v_fmac_f32_e32 v233, v53, v216
	v_fmac_f32_e32 v234, v38, v217
	v_fmac_f32_e32 v235, v39, v217
	v_fmac_f32_e32 v234, v54, v216
	v_fmac_f32_e32 v235, v55, v216
	v_cvt_pk_bf16_f32 v2, v232, v233
	v_cvt_pk_bf16_f32 v3, v234, v235
	s_nop 1
	v_permlane32_swap_b32_e32 v0, v2
	v_permlane32_swap_b32_e32 v1, v3
	global_store_dwordx4 v[236:237], v[0:3], off offset:256
	s_nop 1
	v_fma_f32 v0, v8, v219, 0
	v_fma_f32 v1, v9, v219, 0
	v_fmac_f32_e32 v0, v24, v218
	v_fmac_f32_e32 v1, v25, v218
	v_fma_f32 v2, v10, v219, 0
	v_fma_f32 v3, v11, v219, 0
	v_fmac_f32_e32 v0, v40, v217
	v_fmac_f32_e32 v1, v41, v217
	v_fmac_f32_e32 v2, v26, v218
	v_fmac_f32_e32 v3, v27, v218
	v_fmac_f32_e32 v0, v56, v216
	v_fmac_f32_e32 v1, v57, v216
	v_fmac_f32_e32 v2, v42, v217
	v_fmac_f32_e32 v3, v43, v217
	v_fmac_f32_e32 v2, v58, v216
	v_fmac_f32_e32 v3, v59, v216
	v_cvt_pk_bf16_f32 v0, v0, v1
	v_cvt_pk_bf16_f32 v1, v2, v3
	s_nop 0
	v_fma_f32 v232, v12, v219, 0
	v_fma_f32 v233, v13, v219, 0
	v_fmac_f32_e32 v232, v28, v218
	v_fmac_f32_e32 v233, v29, v218
	v_fma_f32 v234, v14, v219, 0
	v_fma_f32 v235, v15, v219, 0
	v_fmac_f32_e32 v232, v44, v217
	v_fmac_f32_e32 v233, v45, v217
	v_fmac_f32_e32 v234, v30, v218
	v_fmac_f32_e32 v235, v31, v218
	v_fmac_f32_e32 v232, v60, v216
	v_fmac_f32_e32 v233, v61, v216
	v_fmac_f32_e32 v234, v46, v217
	v_fmac_f32_e32 v235, v47, v217
	v_fmac_f32_e32 v234, v62, v216
	v_fmac_f32_e32 v235, v63, v216
	v_cvt_pk_bf16_f32 v2, v232, v233
	v_cvt_pk_bf16_f32 v3, v234, v235
	s_nop 1
	v_permlane32_swap_b32_e32 v0, v2
	v_permlane32_swap_b32_e32 v1, v3
	global_store_dwordx4 v[236:237], v[0:3], off offset:288
	s_nop 1
	v_add_u32_e32 v0, 0x14500, v64
	v_add_u32_e32 v2, 0x14510, v64
	ds_read_b64 v[0:1], v0
	ds_read_b64 v[2:3], v2
	v_add_u32_e32 v196, 0x14520, v64
	ds_read_b64 v[220:221], v196
	v_add_u32_e32 v196, 0x14530, v64
	v_add_u32_e32 v16, 0x14580, v64
	v_add_u32_e32 v18, 0x14590, v64
	ds_read_b64 v[222:223], v196
	ds_read_b64 v[16:17], v16
	ds_read_b64 v[18:19], v18
	s_waitcnt lgkmcnt(4)
	v_mfma_f32_32x32x16_bf16 v[0:15], v[0:3], v[82:85], 0
	v_add_u32_e32 v196, 0x145a0, v64
	v_add_u32_e32 v32, 0x14600, v64
	v_add_u32_e32 v34, 0x14610, v64
	ds_read_b64 v[32:33], v32
	ds_read_b64 v[34:35], v34
	v_add_u32_e32 v48, 0x14680, v64
	v_add_u32_e32 v50, 0x14690, v64
	s_waitcnt lgkmcnt(4)
	v_mfma_f32_32x32x16_bf16 v[0:15], v[220:223], v[78:81], v[0:15]
	ds_read_b64 v[220:221], v196
	v_add_u32_e32 v196, 0x145b0, v64
	ds_read_b64 v[222:223], v196
	v_add_u32_e32 v196, 0x14620, v64
	ds_read_b64 v[48:49], v48
	ds_read_b64 v[50:51], v50
	s_waitcnt lgkmcnt(6)
	v_mfma_f32_32x32x16_bf16 v[16:31], v[16:19], v[98:101], 0
	s_waitcnt lgkmcnt(2)
	v_mfma_f32_32x32x16_bf16 v[16:31], v[220:223], v[90:93], v[16:31]
	ds_read_b64 v[220:221], v240 offset:16928
	v_add_u32_e32 v196, 0x14630, v64
	ds_read_b64 v[222:223], v240 offset:16944
	ds_read_b64 v[224:225], v240 offset:17056
	ds_read_b64 v[226:227], v240 offset:17072
	ds_read_b64 v[228:229], v240 offset:16704
	ds_read_b64 v[230:231], v240 offset:16720
	v_add_u32_e32 v196, 0x146a0, v64
	v_mfma_f32_32x32x16_bf16 v[32:47], v[32:35], v[114:117], 0
	s_waitcnt lgkmcnt(4)
	v_mfma_f32_32x32x16_bf16 v[32:47], v[220:223], v[110:113], v[32:47]
	ds_read_b64 v[220:221], v240 offset:16832
	v_add_u32_e32 v196, 0x146b0, v64
	ds_read_b64 v[222:223], v240 offset:16848
	v_add_u32_e32 v196, 0x14540, v64
	v_mfma_f32_32x32x16_bf16 v[48:63], v[48:51], v[182:185], 0
	s_waitcnt lgkmcnt(4)
	v_mfma_f32_32x32x16_bf16 v[48:63], v[224:227], v[146:149], v[48:63]
	ds_read_b64 v[224:225], v240 offset:16960
	v_add_u32_e32 v196, 0x14550, v64
	ds_read_b64 v[226:227], v240 offset:16976
	v_add_u32_e32 v196, 0x145c0, v64
	s_waitcnt lgkmcnt(4)
	v_mfma_f32_32x32x16_bf16 v[0:15], v[228:231], v[74:77], v[0:15]
	ds_read_b64 v[228:229], v240 offset:17088
	v_add_u32_e32 v196, 0x145d0, v64
	ds_read_b64 v[230:231], v240 offset:17104
	v_add_u32_e32 v196, 0x14640, v64
	s_waitcnt lgkmcnt(4)
; #define LAS __attribute__((address_space(3)))
; #define GAS __attribute__((address_space(1)))
; __device__ __forceinline__ unsigned cvt_pk_bf16(float lo, float hi) { unsigned r; asm volatile("v_cvt_pk_bf16_f32 %0, %1, %2" : "=v"(r) : "v"(lo), "v"(hi)); return r; }
; __device__ __forceinline__ void attn_phase(unsigned char* ws, int l, LAS unsigned char* lds, int G, int bid) {
;     ...
;                 for (int mi = 0; mi < 16 / NQ; ++mi)
; #pragma unroll
;                     for (int qi = 0; qi < NQ; ++qi) {
;                         const int ms = qi * (16 / NQ) + mi;
;                         const LAS unsigned char* vp = lds + (32 * dt + r32) * VST + (16 * ms + 4 * hh) * 2;
;                         const u32x2 lo = *(const LAS u32x2*)vp, hi = *(const LAS u32x2*)(vp + 16);
;                         const u32x4 w = (u32x4){lo.x, lo.y, hi.x, hi.y};
;                         acc[qi] = __builtin_amdgcn_mfma_f32_32x32x16_bf16(__builtin_bit_cast(bf16x8, w), pf[ms], acc[qi], 0, 0, 0);
;                     }
; #pragma unroll
;                 for (int g4 = 0; g4 < 4; ++g4) {
;                     float o4[4];
; #pragma unroll
;                     for (int e = 0; e < 4; ++e) { float v = 0.f;
; #pragma unroll
;                         for (int qi = 0; qi < NQ; ++qi) v = fmaf(acc[qi][4 * g4 + e], fq_[qi], v);
;                         o4[e] = v; }
;                     u32x2 w; w.x = cvt_pk_bf16(o4[0], o4[1]); w.y = cvt_pk_bf16(o4[2], o4[3]);
;                     *(GAS u32x2*)(O + (size_t)qrow * D + h * 256 + 32 * dt + 8 * g4 + 4 * hh) = w;
;                 }
	v_mfma_f32_32x32x16_bf16 v[16:31], v[220:223], v[94:97], v[16:31]
	ds_read_b64 v[220:221], v240 offset:16736
	v_add_u32_e32 v196, 0x14650, v64
	ds_read_b64 v[222:223], v240 offset:16752
	v_add_u32_e32 v196, 0x146c0, v64
	s_waitcnt lgkmcnt(4)
	v_mfma_f32_32x32x16_bf16 v[32:47], v[224:227], v[106:109], v[32:47]
	ds_read_b64 v[224:225], v240 offset:16864
	v_add_u32_e32 v196, 0x146d0, v64
	ds_read_b64 v[226:227], v240 offset:16880
	v_add_u32_e32 v196, 0x14560, v64
	s_waitcnt lgkmcnt(4)
	v_mfma_f32_32x32x16_bf16 v[48:63], v[228:231], v[154:157], v[48:63]
	ds_read_b64 v[228:229], v240 offset:16992
	v_add_u32_e32 v196, 0x14570, v64
	ds_read_b64 v[230:231], v240 offset:17008
	v_add_u32_e32 v196, 0x145e0, v64
	s_waitcnt lgkmcnt(4)
	v_mfma_f32_32x32x16_bf16 v[0:15], v[220:223], v[70:73], v[0:15]
	ds_read_b64 v[220:221], v240 offset:17120
	v_add_u32_e32 v196, 0x145f0, v64
	ds_read_b64 v[222:223], v240 offset:17136
	v_add_u32_e32 v196, 0x14660, v64
	s_nop 7
	v_fma_f32 v0, v0, v219, 0
	s_waitcnt lgkmcnt(4)
	v_mfma_f32_32x32x16_bf16 v[16:31], v[224:227], v[86:89], v[16:31]
	s_nop 0
	v_add_u32_e32 v196, 0x14670, v64
	s_nop 0
	v_add_u32_e32 v196, 0x146e0, v64
	v_fma_f32 v1, v1, v219, 0
	v_fma_f32 v2, v2, v219, 0
	v_fma_f32 v3, v3, v219, 0
	s_waitcnt lgkmcnt(2)
	v_mfma_f32_32x32x16_bf16 v[32:47], v[228:231], v[102:105], v[32:47]
	s_nop 0
	v_add_u32_e32 v196, 0x146f0, v64
	s_nop 0
	v_fmac_f32_e32 v0, v16, v218
	v_fmac_f32_e32 v1, v17, v218
	v_fmac_f32_e32 v2, v18, v218
	v_fmac_f32_e32 v3, v19, v218
	s_waitcnt lgkmcnt(0)
	v_mfma_f32_32x32x16_bf16 v[48:63], v[220:223], v[130:133], v[48:63]
	s_nop 2
	v_fmac_f32_e32 v0, v32, v217
	v_fmac_f32_e32 v1, v33, v217
	v_fmac_f32_e32 v2, v34, v217
	v_fmac_f32_e32 v3, v35, v217
	s_nop 4
	v_fmac_f32_e32 v0, v48, v216
	v_fmac_f32_e32 v1, v49, v216
	v_fmac_f32_e32 v2, v50, v216
	v_fmac_f32_e32 v3, v51, v216
	v_cvt_pk_bf16_f32 v0, v0, v1
	v_cvt_pk_bf16_f32 v1, v2, v3
	s_nop 0
	v_fma_f32 v232, v4, v219, 0
	v_fma_f32 v233, v5, v219, 0
	v_fmac_f32_e32 v232, v20, v218
	v_fmac_f32_e32 v233, v21, v218
	v_fma_f32 v234, v6, v219, 0
	v_fma_f32 v235, v7, v219, 0
	v_fmac_f32_e32 v232, v36, v217
	v_fmac_f32_e32 v233, v37, v217
	v_fmac_f32_e32 v234, v22, v218
	v_fmac_f32_e32 v235, v23, v218
	v_fmac_f32_e32 v232, v52, v216
	v_fmac_f32_e32 v233, v53, v216
	v_fmac_f32_e32 v234, v38, v217
	v_fmac_f32_e32 v235, v39, v217
	v_fmac_f32_e32 v234, v54, v216
	v_fmac_f32_e32 v235, v55, v216
	v_cvt_pk_bf16_f32 v2, v232, v233
	v_cvt_pk_bf16_f32 v3, v234, v235
	s_nop 1
	v_permlane32_swap_b32_e32 v0, v2
	v_permlane32_swap_b32_e32 v1, v3
	global_store_dwordx4 v[236:237], v[0:3], off offset:320
	s_nop 1
	v_fma_f32 v0, v8, v219, 0
	v_fma_f32 v1, v9, v219, 0
	v_fmac_f32_e32 v0, v24, v218
	v_fmac_f32_e32 v1, v25, v218
	v_fma_f32 v2, v10, v219, 0
	v_fma_f32 v3, v11, v219, 0
	v_fmac_f32_e32 v0, v40, v217
	v_fmac_f32_e32 v1, v41, v217
	v_fmac_f32_e32 v2, v26, v218
	v_fmac_f32_e32 v3, v27, v218
	v_fmac_f32_e32 v0, v56, v216
	v_fmac_f32_e32 v1, v57, v216
	v_fmac_f32_e32 v2, v42, v217
	v_fmac_f32_e32 v3, v43, v217
	v_fmac_f32_e32 v2, v58, v216
	v_fmac_f32_e32 v3, v59, v216
	v_cvt_pk_bf16_f32 v0, v0, v1
	v_cvt_pk_bf16_f32 v1, v2, v3
	s_nop 0
	v_fma_f32 v232, v12, v219, 0
	v_fma_f32 v233, v13, v219, 0
	v_fmac_f32_e32 v232, v28, v218
	v_fmac_f32_e32 v233, v29, v218
	v_fma_f32 v234, v14, v219, 0
	v_fma_f32 v235, v15, v219, 0
	v_fmac_f32_e32 v232, v44, v217
	v_fmac_f32_e32 v233, v45, v217
	v_fmac_f32_e32 v234, v30, v218
	v_fmac_f32_e32 v235, v31, v218
	v_fmac_f32_e32 v232, v60, v216
	v_fmac_f32_e32 v233, v61, v216
	v_fmac_f32_e32 v234, v46, v217
	v_fmac_f32_e32 v235, v47, v217
	v_fmac_f32_e32 v234, v62, v216
	v_fmac_f32_e32 v235, v63, v216
	v_cvt_pk_bf16_f32 v2, v232, v233
	v_cvt_pk_bf16_f32 v3, v234, v235
	s_nop 1
	v_permlane32_swap_b32_e32 v0, v2
	v_permlane32_swap_b32_e32 v1, v3
	global_store_dwordx4 v[236:237], v[0:3], off offset:352
	s_nop 1
	v_add_u32_e32 v0, 0x18600, v64
	v_add_u32_e32 v2, 0x18610, v64
	ds_read_b64 v[0:1], v0
	ds_read_b64 v[2:3], v2
	v_add_u32_e32 v196, 0x18620, v64
	ds_read_b64 v[220:221], v196
	v_add_u32_e32 v196, 0x18630, v64
	v_add_u32_e32 v16, 0x18680, v64
	v_add_u32_e32 v18, 0x18690, v64
	ds_read_b64 v[222:223], v196
	ds_read_b64 v[16:17], v16
	ds_read_b64 v[18:19], v18
	s_waitcnt lgkmcnt(4)
	v_mfma_f32_32x32x16_bf16 v[0:15], v[0:3], v[82:85], 0
	v_add_u32_e32 v196, 0x186a0, v64
	v_add_u32_e32 v32, 0x18700, v64
	v_add_u32_e32 v34, 0x18710, v64
	ds_read_b64 v[32:33], v32
	ds_read_b64 v[34:35], v34
	v_add_u32_e32 v48, 0x18780, v64
	v_add_u32_e32 v50, 0x18790, v64
	s_waitcnt lgkmcnt(4)
	v_mfma_f32_32x32x16_bf16 v[0:15], v[220:223], v[78:81], v[0:15]
	ds_read_b64 v[220:221], v196
	v_add_u32_e32 v196, 0x186b0, v64
	ds_read_b64 v[222:223], v196
	v_add_u32_e32 v196, 0x18720, v64
	ds_read_b64 v[48:49], v48
	ds_read_b64 v[50:51], v50
	s_waitcnt lgkmcnt(6)
	v_mfma_f32_32x32x16_bf16 v[16:31], v[16:19], v[98:101], 0
	s_waitcnt lgkmcnt(2)
	v_mfma_f32_32x32x16_bf16 v[16:31], v[220:223], v[90:93], v[16:31]
	ds_read_b64 v[220:221], v240 offset:33568
	v_add_u32_e32 v196, 0x18730, v64
	ds_read_b64 v[222:223], v240 offset:33584
	ds_read_b64 v[224:225], v240 offset:33696
	ds_read_b64 v[226:227], v240 offset:33712
	ds_read_b64 v[228:229], v240 offset:33344
	ds_read_b64 v[230:231], v240 offset:33360
	v_add_u32_e32 v196, 0x187a0, v64
	v_mfma_f32_32x32x16_bf16 v[32:47], v[32:35], v[114:117], 0
	s_waitcnt lgkmcnt(4)
	v_mfma_f32_32x32x16_bf16 v[32:47], v[220:223], v[110:113], v[32:47]
	ds_read_b64 v[220:221], v240 offset:33472
	v_add_u32_e32 v196, 0x187b0, v64
	ds_read_b64 v[222:223], v240 offset:33488
	v_add_u32_e32 v196, 0x18640, v64
	v_mfma_f32_32x32x16_bf16 v[48:63], v[48:51], v[182:185], 0
	s_waitcnt lgkmcnt(4)
; #define LAS __attribute__((address_space(3)))
; #define GAS __attribute__((address_space(1)))
; __device__ __forceinline__ unsigned cvt_pk_bf16(float lo, float hi) { unsigned r; asm volatile("v_cvt_pk_bf16_f32 %0, %1, %2" : "=v"(r) : "v"(lo), "v"(hi)); return r; }
; __device__ __forceinline__ void attn_phase(unsigned char* ws, int l, LAS unsigned char* lds, int G, int bid) {
;     ...
;                 for (int mi = 0; mi < 16 / NQ; ++mi)
; #pragma unroll
;                     for (int qi = 0; qi < NQ; ++qi) {
;                         const int ms = qi * (16 / NQ) + mi;
;                         const LAS unsigned char* vp = lds + (32 * dt + r32) * VST + (16 * ms + 4 * hh) * 2;
;                         const u32x2 lo = *(const LAS u32x2*)vp, hi = *(const LAS u32x2*)(vp + 16);
;                         const u32x4 w = (u32x4){lo.x, lo.y, hi.x, hi.y};
;                         acc[qi] = __builtin_amdgcn_mfma_f32_32x32x16_bf16(__builtin_bit_cast(bf16x8, w), pf[ms], acc[qi], 0, 0, 0);
;                     }
; #pragma unroll
;                 for (int g4 = 0; g4 < 4; ++g4) {
;                     float o4[4];
; #pragma unroll
;                     for (int e = 0; e < 4; ++e) { float v = 0.f;
; #pragma unroll
;                         for (int qi = 0; qi < NQ; ++qi) v = fmaf(acc[qi][4 * g4 + e], fq_[qi], v);
;                         o4[e] = v; }
;                     u32x2 w; w.x = cvt_pk_bf16(o4[0], o4[1]); w.y = cvt_pk_bf16(o4[2], o4[3]);
;                     *(GAS u32x2*)(O + (size_t)qrow * D + h * 256 + 32 * dt + 8 * g4 + 4 * hh) = w;
;                 }
	v_mfma_f32_32x32x16_bf16 v[48:63], v[224:227], v[146:149], v[48:63]
	ds_read_b64 v[224:225], v240 offset:33600
	v_add_u32_e32 v196, 0x18650, v64
	ds_read_b64 v[226:227], v240 offset:33616
	v_add_u32_e32 v196, 0x186c0, v64
	s_waitcnt lgkmcnt(4)
	v_mfma_f32_32x32x16_bf16 v[0:15], v[228:231], v[74:77], v[0:15]
	ds_read_b64 v[228:229], v240 offset:33728
	v_add_u32_e32 v196, 0x186d0, v64
	ds_read_b64 v[230:231], v240 offset:33744
	v_add_u32_e32 v196, 0x18740, v64
	s_waitcnt lgkmcnt(4)
	v_mfma_f32_32x32x16_bf16 v[16:31], v[220:223], v[94:97], v[16:31]
	ds_read_b64 v[220:221], v240 offset:33376
	v_add_u32_e32 v196, 0x18750, v64
	ds_read_b64 v[222:223], v240 offset:33392
	v_add_u32_e32 v196, 0x187c0, v64
	s_waitcnt lgkmcnt(4)
	v_mfma_f32_32x32x16_bf16 v[32:47], v[224:227], v[106:109], v[32:47]
	ds_read_b64 v[224:225], v240 offset:33504
	v_add_u32_e32 v196, 0x187d0, v64
	ds_read_b64 v[226:227], v240 offset:33520
	v_add_u32_e32 v196, 0x18660, v64
	s_waitcnt lgkmcnt(4)
	v_mfma_f32_32x32x16_bf16 v[48:63], v[228:231], v[154:157], v[48:63]
	ds_read_b64 v[228:229], v240 offset:33632
	v_add_u32_e32 v196, 0x18670, v64
	ds_read_b64 v[230:231], v240 offset:33648
	v_add_u32_e32 v196, 0x186e0, v64
	s_waitcnt lgkmcnt(4)
	v_mfma_f32_32x32x16_bf16 v[0:15], v[220:223], v[70:73], v[0:15]
	ds_read_b64 v[220:221], v240 offset:33760
	v_add_u32_e32 v196, 0x186f0, v64
	ds_read_b64 v[222:223], v240 offset:33776
	v_add_u32_e32 v196, 0x18760, v64
	s_nop 7
	v_fma_f32 v0, v0, v219, 0
	s_waitcnt lgkmcnt(4)
	v_mfma_f32_32x32x16_bf16 v[16:31], v[224:227], v[86:89], v[16:31]
	s_nop 0
	v_add_u32_e32 v196, 0x18770, v64
	s_nop 0
	v_add_u32_e32 v196, 0x187e0, v64
	v_fma_f32 v1, v1, v219, 0
	v_fma_f32 v2, v2, v219, 0
	v_fma_f32 v3, v3, v219, 0
	s_waitcnt lgkmcnt(2)
	v_mfma_f32_32x32x16_bf16 v[32:47], v[228:231], v[102:105], v[32:47]
	s_nop 0
	v_add_u32_e32 v196, 0x187f0, v64
	s_nop 0
	v_fmac_f32_e32 v0, v16, v218
	v_fmac_f32_e32 v1, v17, v218
	v_fmac_f32_e32 v2, v18, v218
	v_fmac_f32_e32 v3, v19, v218
	s_waitcnt lgkmcnt(0)
	v_mfma_f32_32x32x16_bf16 v[48:63], v[220:223], v[130:133], v[48:63]
	s_nop 2
	v_fmac_f32_e32 v0, v32, v217
	v_fmac_f32_e32 v1, v33, v217
	v_fmac_f32_e32 v2, v34, v217
	v_fmac_f32_e32 v3, v35, v217
	s_nop 4
	v_fmac_f32_e32 v0, v48, v216
	v_fmac_f32_e32 v1, v49, v216
	v_fmac_f32_e32 v2, v50, v216
	v_fmac_f32_e32 v3, v51, v216
	v_cvt_pk_bf16_f32 v0, v0, v1
	v_cvt_pk_bf16_f32 v1, v2, v3
	s_nop 0
	v_fma_f32 v232, v4, v219, 0
	v_fma_f32 v233, v5, v219, 0
	v_fmac_f32_e32 v232, v20, v218
	v_fmac_f32_e32 v233, v21, v218
	v_fma_f32 v234, v6, v219, 0
	v_fma_f32 v235, v7, v219, 0
	v_fmac_f32_e32 v232, v36, v217
	v_fmac_f32_e32 v233, v37, v217
	v_fmac_f32_e32 v234, v22, v218
	v_fmac_f32_e32 v235, v23, v218
	v_fmac_f32_e32 v232, v52, v216
	v_fmac_f32_e32 v233, v53, v216
	v_fmac_f32_e32 v234, v38, v217
	v_fmac_f32_e32 v235, v39, v217
	v_fmac_f32_e32 v234, v54, v216
	v_fmac_f32_e32 v235, v55, v216
	v_cvt_pk_bf16_f32 v2, v232, v233
	v_cvt_pk_bf16_f32 v3, v234, v235
	s_nop 1
	v_permlane32_swap_b32_e32 v0, v2
	v_permlane32_swap_b32_e32 v1, v3
	global_store_dwordx4 v[236:237], v[0:3], off offset:384
	s_nop 1
	v_fma_f32 v0, v8, v219, 0
	v_fma_f32 v1, v9, v219, 0
	v_fmac_f32_e32 v0, v24, v218
	v_fmac_f32_e32 v1, v25, v218
	v_fma_f32 v2, v10, v219, 0
	v_fma_f32 v3, v11, v219, 0
	v_fmac_f32_e32 v0, v40, v217
	v_fmac_f32_e32 v1, v41, v217
	v_fmac_f32_e32 v2, v26, v218
	v_fmac_f32_e32 v3, v27, v218
	v_fmac_f32_e32 v0, v56, v216
	v_fmac_f32_e32 v1, v57, v216
	v_fmac_f32_e32 v2, v42, v217
	v_fmac_f32_e32 v3, v43, v217
	v_fmac_f32_e32 v2, v58, v216
	v_fmac_f32_e32 v3, v59, v216
	v_cvt_pk_bf16_f32 v0, v0, v1
	v_cvt_pk_bf16_f32 v1, v2, v3
	s_nop 0
	v_fma_f32 v232, v12, v219, 0
	v_fma_f32 v233, v13, v219, 0
	v_fmac_f32_e32 v232, v28, v218
	v_fmac_f32_e32 v233, v29, v218
	v_fma_f32 v234, v14, v219, 0
	v_fma_f32 v235, v15, v219, 0
	v_fmac_f32_e32 v232, v44, v217
	v_fmac_f32_e32 v233, v45, v217
	v_fmac_f32_e32 v234, v30, v218
	v_fmac_f32_e32 v235, v31, v218
	v_fmac_f32_e32 v232, v60, v216
	v_fmac_f32_e32 v233, v61, v216
	v_fmac_f32_e32 v234, v46, v217
	v_fmac_f32_e32 v235, v47, v217
	v_fmac_f32_e32 v234, v62, v216
	v_fmac_f32_e32 v235, v63, v216
	v_cvt_pk_bf16_f32 v2, v232, v233
	v_cvt_pk_bf16_f32 v3, v234, v235
	s_nop 1
	v_permlane32_swap_b32_e32 v0, v2
	v_permlane32_swap_b32_e32 v1, v3
	global_store_dwordx4 v[236:237], v[0:3], off offset:416
	s_nop 1
	v_add_u32_e32 v0, 0x1c700, v64
	v_add_u32_e32 v2, 0x1c710, v64
	ds_read_b64 v[0:1], v0
	ds_read_b64 v[2:3], v2
	v_add_u32_e32 v16, 0x1c780, v64
	v_add_u32_e32 v18, 0x1c790, v64
	ds_read_b64 v[16:17], v16
	ds_read_b64 v[18:19], v18
	v_add_u32_e32 v32, 0x1c800, v64
	v_add_u32_e32 v34, 0x1c810, v64
	s_waitcnt lgkmcnt(2)
	v_mfma_f32_32x32x16_bf16 v[0:15], v[0:3], v[82:85], 0
	v_add_u32_e32 v82, 0x1c720, v64
	v_add_u32_e32 v84, 0x1c730, v64
	ds_read_b64 v[82:83], v82
	ds_read_b64 v[84:85], v84
	ds_read_b64 v[32:33], v32
	ds_read_b64 v[34:35], v34
	v_add_u32_e32 v48, 0x1c880, v64
	s_waitcnt lgkmcnt(2)
; #define LAS __attribute__((address_space(3)))
; #define GAS __attribute__((address_space(1)))
; __device__ __forceinline__ unsigned cvt_pk_bf16(float lo, float hi) { unsigned r; asm volatile("v_cvt_pk_bf16_f32 %0, %1, %2" : "=v"(r) : "v"(lo), "v"(hi)); return r; }
; __device__ __forceinline__ void attn_phase(unsigned char* ws, int l, LAS unsigned char* lds, int G, int bid) {
;     ...
;                 for (int mi = 0; mi < 16 / NQ; ++mi)
; #pragma unroll
;                     for (int qi = 0; qi < NQ; ++qi) {
;                         const int ms = qi * (16 / NQ) + mi;
;                         const LAS unsigned char* vp = lds + (32 * dt + r32) * VST + (16 * ms + 4 * hh) * 2;
;                         const u32x2 lo = *(const LAS u32x2*)vp, hi = *(const LAS u32x2*)(vp + 16);
;                         const u32x4 w = (u32x4){lo.x, lo.y, hi.x, hi.y};
;                         acc[qi] = __builtin_amdgcn_mfma_f32_32x32x16_bf16(__builtin_bit_cast(bf16x8, w), pf[ms], acc[qi], 0, 0, 0);
;                     }
; #pragma unroll
;                 for (int g4 = 0; g4 < 4; ++g4) {
;                     float o4[4];
; #pragma unroll
;                     for (int e = 0; e < 4; ++e) { float v = 0.f;
; #pragma unroll
;                         for (int qi = 0; qi < NQ; ++qi) v = fmaf(acc[qi][4 * g4 + e], fq_[qi], v);
;                         o4[e] = v; }
;                     u32x2 w; w.x = cvt_pk_bf16(o4[0], o4[1]); w.y = cvt_pk_bf16(o4[2], o4[3]);
;                     *(GAS u32x2*)(O + (size_t)qrow * D + h * 256 + 32 * dt + 8 * g4 + 4 * hh) = w;
;                 }
	v_mfma_f32_32x32x16_bf16 v[0:15], v[82:85], v[78:81], v[0:15]
	v_add_u32_e32 v78, 0x1c7a0, v64
	v_add_u32_e32 v80, 0x1c7b0, v64
	ds_read_b64 v[78:79], v78
	ds_read_b64 v[80:81], v80
	v_add_u32_e32 v50, 0x1c890, v64
	ds_read_b64 v[48:49], v48
	ds_read_b64 v[50:51], v50
	v_mfma_f32_32x32x16_bf16 v[16:31], v[16:19], v[98:101], 0
	s_waitcnt lgkmcnt(2)
	v_mfma_f32_32x32x16_bf16 v[16:31], v[78:81], v[90:93], v[16:31]
	v_add_u32_e32 v78, 0x1c820, v64
	v_add_u32_e32 v80, 0x1c830, v64
	ds_read_b64 v[78:79], v78
	ds_read_b64 v[80:81], v80
	v_mfma_f32_32x32x16_bf16 v[32:47], v[32:35], v[114:117], 0
	s_waitcnt lgkmcnt(0)
	v_mfma_f32_32x32x16_bf16 v[32:47], v[78:81], v[110:113], v[32:47]
	v_add_u32_e32 v78, 0x1c8a0, v64
	v_add_u32_e32 v80, 0x1c8b0, v64
	ds_read_b64 v[78:79], v78
	ds_read_b64 v[80:81], v80
	v_mfma_f32_32x32x16_bf16 v[48:63], v[48:51], v[182:185], 0
	s_waitcnt lgkmcnt(0)
	v_mfma_f32_32x32x16_bf16 v[48:63], v[78:81], v[146:149], v[48:63]
	v_add_u32_e32 v78, 0x1c740, v64
	v_add_u32_e32 v80, 0x1c750, v64
	ds_read_b64 v[78:79], v78
	ds_read_b64 v[80:81], v80
	s_waitcnt lgkmcnt(0)
	v_mfma_f32_32x32x16_bf16 v[0:15], v[78:81], v[74:77], v[0:15]
	v_add_u32_e32 v74, 0x1c7c0, v64
	v_add_u32_e32 v76, 0x1c7d0, v64
	ds_read_b64 v[74:75], v74
	ds_read_b64 v[76:77], v76
	s_waitcnt lgkmcnt(0)
	v_mfma_f32_32x32x16_bf16 v[16:31], v[74:77], v[94:97], v[16:31]
	v_add_u32_e32 v74, 0x1c840, v64
	v_add_u32_e32 v76, 0x1c850, v64
	ds_read_b64 v[74:75], v74
	ds_read_b64 v[76:77], v76
	s_waitcnt lgkmcnt(0)
	v_mfma_f32_32x32x16_bf16 v[32:47], v[74:77], v[106:109], v[32:47]
	v_add_u32_e32 v74, 0x1c8c0, v64
	v_add_u32_e32 v76, 0x1c8d0, v64
	ds_read_b64 v[74:75], v74
	ds_read_b64 v[76:77], v76
	s_waitcnt lgkmcnt(0)
	v_mfma_f32_32x32x16_bf16 v[48:63], v[74:77], v[154:157], v[48:63]
	v_add_u32_e32 v74, 0x1c760, v64
	v_add_u32_e32 v76, 0x1c770, v64
	ds_read_b64 v[74:75], v74
	ds_read_b64 v[76:77], v76
	s_waitcnt lgkmcnt(0)
	v_mfma_f32_32x32x16_bf16 v[0:15], v[74:77], v[70:73], v[0:15]
	v_add_u32_e32 v70, 0x1c7e0, v64
	v_add_u32_e32 v72, 0x1c7f0, v64
	ds_read_b64 v[70:71], v70
	ds_read_b64 v[72:73], v72
	s_nop 7
	v_fma_f32 v0, v0, v219, 0
	s_waitcnt lgkmcnt(0)
	v_mfma_f32_32x32x16_bf16 v[16:31], v[70:73], v[86:89], v[16:31]
	v_add_u32_e32 v70, 0x1c860, v64
	v_add_u32_e32 v72, 0x1c870, v64
	ds_read_b64 v[70:71], v70
	ds_read_b64 v[72:73], v72
	v_fma_f32 v1, v1, v219, 0
	v_fma_f32 v2, v2, v219, 0
	v_fma_f32 v3, v3, v219, 0
	s_waitcnt lgkmcnt(0)
	v_mfma_f32_32x32x16_bf16 v[32:47], v[70:73], v[102:105], v[32:47]
	v_add_u32_e32 v70, 0x1c8e0, v64
	v_add_u32_e32 v64, 0x1c8f0, v64
	ds_read_b64 v[70:71], v70
	ds_read_b64 v[72:73], v64
	v_fmac_f32_e32 v0, v16, v218
	v_fmac_f32_e32 v1, v17, v218
	v_fmac_f32_e32 v2, v18, v218
	s_waitcnt lgkmcnt(0)
	v_mfma_f32_32x32x16_bf16 v[48:63], v[70:73], v[130:133], v[48:63]
	s_nop 2
	v_fmac_f32_e32 v0, v32, v217
	v_fmac_f32_e32 v1, v33, v217
	v_fmac_f32_e32 v3, v19, v218
	v_fmac_f32_e32 v2, v34, v217
	v_fmac_f32_e32 v3, v35, v217
	s_nop 3
	v_fmac_f32_e32 v0, v48, v216
	v_fmac_f32_e32 v1, v49, v216
	v_fmac_f32_e32 v2, v50, v216
	v_fmac_f32_e32 v3, v51, v216
	v_cvt_pk_bf16_f32 v0, v0, v1
	v_cvt_pk_bf16_f32 v1, v2, v3
	s_nop 0
	v_fma_f32 v232, v4, v219, 0
	v_fma_f32 v233, v5, v219, 0
	v_fmac_f32_e32 v232, v20, v218
	v_fmac_f32_e32 v233, v21, v218
	v_fma_f32 v234, v6, v219, 0
	v_fma_f32 v235, v7, v219, 0
	v_fmac_f32_e32 v232, v36, v217
	v_fmac_f32_e32 v233, v37, v217
	v_fmac_f32_e32 v234, v22, v218
	v_fmac_f32_e32 v235, v23, v218
	v_fmac_f32_e32 v232, v52, v216
	v_fmac_f32_e32 v233, v53, v216
	v_fmac_f32_e32 v234, v38, v217
	v_fmac_f32_e32 v235, v39, v217
	v_fmac_f32_e32 v234, v54, v216
	v_fmac_f32_e32 v235, v55, v216
	v_cvt_pk_bf16_f32 v2, v232, v233
	v_cvt_pk_bf16_f32 v3, v234, v235
	s_nop 1
	v_permlane32_swap_b32_e32 v0, v2
	v_permlane32_swap_b32_e32 v1, v3
	global_store_dwordx4 v[236:237], v[0:3], off offset:448
	s_nop 1
	v_fma_f32 v0, v8, v219, 0
	v_fma_f32 v1, v9, v219, 0
	v_fmac_f32_e32 v0, v24, v218
	v_fmac_f32_e32 v1, v25, v218
	v_fma_f32 v2, v10, v219, 0
	v_fma_f32 v3, v11, v219, 0
	v_fmac_f32_e32 v0, v40, v217
	v_fmac_f32_e32 v1, v41, v217
	v_fmac_f32_e32 v2, v26, v218
	v_fmac_f32_e32 v3, v27, v218
	v_fmac_f32_e32 v0, v56, v216
	v_fmac_f32_e32 v1, v57, v216
	v_fmac_f32_e32 v2, v42, v217
	v_fmac_f32_e32 v3, v43, v217
	v_fmac_f32_e32 v2, v58, v216
	v_fmac_f32_e32 v3, v59, v216
	v_cvt_pk_bf16_f32 v0, v0, v1
	v_cvt_pk_bf16_f32 v1, v2, v3
	s_nop 0
	v_fma_f32 v232, v12, v219, 0
	v_fma_f32 v233, v13, v219, 0
	v_fmac_f32_e32 v232, v28, v218
	v_fmac_f32_e32 v233, v29, v218
	v_fma_f32 v234, v14, v219, 0
	v_fma_f32 v235, v15, v219, 0
	v_fmac_f32_e32 v232, v44, v217
	v_fmac_f32_e32 v233, v45, v217
	v_fmac_f32_e32 v234, v30, v218
	v_fmac_f32_e32 v235, v31, v218
	v_fmac_f32_e32 v232, v60, v216
	v_fmac_f32_e32 v233, v61, v216
	v_fmac_f32_e32 v234, v46, v217
	v_fmac_f32_e32 v235, v47, v217
	v_fmac_f32_e32 v234, v62, v216
	v_fmac_f32_e32 v235, v63, v216
	v_cvt_pk_bf16_f32 v2, v232, v233
	v_cvt_pk_bf16_f32 v3, v234, v235
	s_nop 1
	v_permlane32_swap_b32_e32 v0, v2
	v_permlane32_swap_b32_e32 v1, v3
	global_store_dwordx4 v[236:237], v[0:3], off offset:480
	s_nop 1
	s_branch .LBB0_868

; #define GAS __attribute__((address_space(1)))
; __global__ void __launch_bounds__(512, 2) hybrid_fwd(Args a) {
;     ...
;             for (int r = bb * 8 + wave; r < TS; r += gg * 8) {
;                 GAS f32x4* sp = (GAS f32x4*)(scr + (size_t)r * D) + lane4; GAS u32x2* xp = (GAS u32x2*)((bf16_t*)(wsp + WS_XB) + (size_t)(TP + r) * D) + lane4;
;                 float ssum = 0.f;
; #pragma unroll
;                 for (int j = 0; j < 4; ++j) { const f32x4 d = (sp[64 * j] + sp[64 * j + (size_t)TS * D / 4]) + (sp[64 * j + 2 * ((size_t)TS * D / 4)] + sp[64 * j + 3 * ((size_t)TS * D / 4)]); const u32x2 w = xp[64 * j];
.LBB0_1212:
	v_add_co_u32_e32 v2, vcc, 0xff400000, v0
	s_waitcnt lgkmcnt(0)
	s_nop 0
	v_addc_co_u32_e32 v3, vcc, -1, v1, vcc
	v_add_co_u32_e32 v4, vcc, 0xff800000, v0
	global_load_dwordx4 v[10:13], v[2:3], off offset:-3072
	s_nop 0
	v_addc_co_u32_e32 v5, vcc, -1, v1, vcc
	global_load_dwordx4 v[14:17], v[4:5], off offset:-3072
	v_add_co_u32_e32 v6, vcc, 0xffc00000, v0
	s_nop 1
	v_addc_co_u32_e32 v7, vcc, -1, v1, vcc
	global_load_dwordx4 v[104:107], v[6:7], off offset:-3072
	global_load_dwordx4 v[108:111], v[0:1], off offset:-3072
	global_load_dwordx2 v[112:113], v8, s[16:17]
	global_load_dwordx4 v[114:117], v[2:3], off offset:-2048
	global_load_dwordx4 v[118:121], v[4:5], off offset:-2048
	global_load_dwordx4 v[122:125], v[6:7], off offset:-2048
	global_load_dwordx4 v[126:129], v[0:1], off offset:-2048
	global_load_dwordx2 v[130:131], v8, s[16:17] offset:512
	global_load_dwordx4 v[132:135], v[2:3], off offset:-1024
	global_load_dwordx4 v[136:139], v[4:5], off offset:-1024
	global_load_dwordx4 v[140:143], v[6:7], off offset:-1024
	global_load_dwordx4 v[144:147], v[0:1], off offset:-1024
	global_load_dwordx2 v[148:149], v8, s[16:17] offset:1024
	global_load_dwordx4 v[150:153], v[2:3], off
	global_load_dwordx4 v[154:157], v[4:5], off
	global_load_dwordx4 v[158:161], v[6:7], off
	global_load_dwordx4 v[162:165], v[0:1], off
	global_load_dwordx2 v[166:167], v8, s[16:17] offset:1536
	s_waitcnt vmcnt(0)
; __device__ __forceinline__ unsigned cvt_pk_bf16(float lo, float hi) { unsigned r; asm volatile("v_cvt_pk_bf16_f32 %0, %1, %2" : "=v"(r) : "v"(lo), "v"(hi)); return r; }
; __device__ __forceinline__ float bf_lo(unsigned w) { return __uint_as_float(w << 16); }
; __device__ __forceinline__ float bf_hi(unsigned w) { return __uint_as_float(w & 0xffff0000u); }
; __device__ __forceinline__ float wave_sum(float v) {
; #pragma unroll
;     for (int o = 1; o < 64; o <<= 1) v += __shfl_xor(v, o);
;     return v;
; __global__ void __launch_bounds__(512, 2) hybrid_fwd(Args a) {
;     ...
;                 for (int j = 0; j < 4; ++j) { const f32x4 d = (sp[64 * j] + sp[64 * j + (size_t)TS * D / 4]) + (sp[64 * j + 2 * ((size_t)TS * D / 4)] + sp[64 * j + 3 * ((size_t)TS * D / 4)]); const u32x2 w = xp[64 * j];
;                     const f32x4 x = (f32x4){bf_lo(w.x), bf_hi(w.x), bf_lo(w.y), bf_hi(w.y)} + d;
;                     ssum += (x[0] * x[0] + x[1] * x[1]) + (x[2] * x[2] + x[3] * x[3]);
;                     u32x2 o; o.x = cvt_pk_bf16(x[0], x[1]); o.y = cvt_pk_bf16(x[2], x[3]); xp[64 * j] = o; }
;                 ssum = wave_sum(ssum);
;                 if (lane4 == 0) ss3[TP + r] = ssum;
	v_pk_add_f32 v[18:19], v[12:13], v[16:17]
	s_nop 0
	v_pk_add_f32 v[20:21], v[10:11], v[14:15]
	s_nop 1
	v_mov_b64_e32 v[10:11], v[104:105]
	v_mov_b64_e32 v[12:13], v[106:107]
	s_nop 1
	v_mov_b64_e32 v[14:15], v[108:109]
	v_mov_b64_e32 v[16:17], v[110:111]
	s_nop 0
	v_pk_add_f32 v[10:11], v[10:11], v[14:15]
	s_nop 1
	v_mov_b64_e32 v[14:15], v[112:113]
	v_pk_add_f32 v[12:13], v[12:13], v[16:17]
	v_pk_add_f32 v[10:11], v[20:21], v[10:11]
	v_pk_add_f32 v[12:13], v[18:19], v[12:13]
	s_nop 0
	v_lshlrev_b32_e32 v16, 16, v14
	v_and_b32_e32 v17, 0xffff0000, v14
	v_lshlrev_b32_e32 v14, 16, v15
	v_and_b32_e32 v15, 0xffff0000, v15
	v_pk_add_f32 v[12:13], v[12:13], v[14:15]
	v_pk_add_f32 v[10:11], v[10:11], v[16:17]
	v_mul_f32_e32 v14, v13, v13
	v_mul_f32_e32 v9, v11, v11
	v_fmac_f32_e32 v9, v10, v10
	v_fmac_f32_e32 v14, v12, v12
	v_cvt_pk_bf16_f32 v10, v10, v11
	v_cvt_pk_bf16_f32 v11, v12, v13
	global_store_dwordx2 v8, v[10:11], s[16:17]
	v_add_f32_e32 v9, v9, v14
	s_nop 1
	v_mov_b64_e32 v[10:11], v[114:115]
	v_mov_b64_e32 v[12:13], v[116:117]
	s_nop 1
	v_mov_b64_e32 v[14:15], v[118:119]
	v_mov_b64_e32 v[16:17], v[120:121]
	s_nop 0
	v_pk_add_f32 v[18:19], v[12:13], v[16:17]
	v_pk_add_f32 v[20:21], v[10:11], v[14:15]
	s_nop 1
	v_mov_b64_e32 v[10:11], v[122:123]
	v_mov_b64_e32 v[12:13], v[124:125]
	s_nop 1
	v_mov_b64_e32 v[14:15], v[126:127]
	v_mov_b64_e32 v[16:17], v[128:129]
	s_nop 0
	v_pk_add_f32 v[10:11], v[10:11], v[14:15]
	s_nop 1
	v_mov_b64_e32 v[14:15], v[130:131]
	v_pk_add_f32 v[12:13], v[12:13], v[16:17]
	v_pk_add_f32 v[10:11], v[20:21], v[10:11]
	v_pk_add_f32 v[12:13], v[18:19], v[12:13]
	s_nop 0
	v_lshlrev_b32_e32 v16, 16, v14
	v_and_b32_e32 v17, 0xffff0000, v14
	v_lshlrev_b32_e32 v14, 16, v15
	v_and_b32_e32 v15, 0xffff0000, v15
	v_pk_add_f32 v[12:13], v[12:13], v[14:15]
	v_pk_add_f32 v[10:11], v[10:11], v[16:17]
	v_mul_f32_e32 v15, v13, v13
	v_mul_f32_e32 v14, v11, v11
	v_fmac_f32_e32 v14, v10, v10
	v_fmac_f32_e32 v15, v12, v12
	v_add_f32_e32 v14, v14, v15
	v_cvt_pk_bf16_f32 v10, v10, v11
	v_cvt_pk_bf16_f32 v11, v12, v13
	global_store_dwordx2 v8, v[10:11], s[16:17] offset:512
	v_add_f32_e32 v9, v9, v14
	s_nop 1
	v_mov_b64_e32 v[10:11], v[132:133]
	v_mov_b64_e32 v[12:13], v[134:135]
	s_nop 1
	v_mov_b64_e32 v[14:15], v[136:137]
	v_mov_b64_e32 v[16:17], v[138:139]
	s_nop 0
	v_pk_add_f32 v[18:19], v[12:13], v[16:17]
	v_pk_add_f32 v[20:21], v[10:11], v[14:15]
	s_nop 1
	v_mov_b64_e32 v[10:11], v[140:141]
	v_mov_b64_e32 v[12:13], v[142:143]
	s_nop 1
	v_mov_b64_e32 v[14:15], v[144:145]
	v_mov_b64_e32 v[16:17], v[146:147]
	s_nop 0
	v_pk_add_f32 v[10:11], v[10:11], v[14:15]
	s_nop 1
	v_mov_b64_e32 v[14:15], v[148:149]
	v_pk_add_f32 v[12:13], v[12:13], v[16:17]
	v_pk_add_f32 v[10:11], v[20:21], v[10:11]
	v_pk_add_f32 v[12:13], v[18:19], v[12:13]
	s_nop 0
	v_lshlrev_b32_e32 v16, 16, v14
	v_and_b32_e32 v17, 0xffff0000, v14
	v_lshlrev_b32_e32 v14, 16, v15
	v_and_b32_e32 v15, 0xffff0000, v15
	v_pk_add_f32 v[10:11], v[10:11], v[16:17]
	v_pk_add_f32 v[12:13], v[12:13], v[14:15]
	v_mul_f32_e32 v14, v11, v11
	v_fmac_f32_e32 v14, v10, v10
	v_mul_f32_e32 v15, v13, v13
	v_cvt_pk_bf16_f32 v10, v10, v11
	v_cvt_pk_bf16_f32 v11, v12, v13
	global_store_dwordx2 v8, v[10:11], s[16:17] offset:1024
	v_fmac_f32_e32 v15, v12, v12
	s_nop 1
	v_mov_b64_e32 v[10:11], v[150:151]
	v_mov_b64_e32 v[12:13], v[152:153]
	s_nop 0
	s_nop 1
	v_mov_b64_e32 v[2:3], v[154:155]
	v_mov_b64_e32 v[4:5], v[156:157]
	v_add_f32_e32 v14, v14, v15
	v_add_f32_e32 v9, v9, v14
	s_nop 0
	v_pk_add_f32 v[14:15], v[12:13], v[4:5]
	v_pk_add_f32 v[16:17], v[10:11], v[2:3]
	s_nop 1
	v_mov_b64_e32 v[2:3], v[158:159]
	v_mov_b64_e32 v[4:5], v[160:161]
	s_nop 1
	v_mov_b64_e32 v[10:11], v[162:163]
	v_mov_b64_e32 v[12:13], v[164:165]
	s_nop 0
	v_pk_add_f32 v[2:3], v[2:3], v[10:11]
	s_nop 1
	v_mov_b64_e32 v[6:7], v[166:167]
	v_pk_add_f32 v[4:5], v[4:5], v[12:13]
	v_pk_add_f32 v[2:3], v[16:17], v[2:3]
	v_pk_add_f32 v[4:5], v[14:15], v[4:5]
	s_nop 0
	v_lshlrev_b32_e32 v10, 16, v6
	v_and_b32_e32 v11, 0xffff0000, v6
	v_lshlrev_b32_e32 v6, 16, v7
	v_and_b32_e32 v7, 0xffff0000, v7
	v_pk_add_f32 v[2:3], v[2:3], v[10:11]
	v_pk_add_f32 v[4:5], v[4:5], v[6:7]
	v_mul_f32_e32 v6, v3, v3
	v_fmac_f32_e32 v6, v2, v2
	v_cvt_pk_bf16_f32 v2, v2, v3
	v_cvt_pk_bf16_f32 v3, v4, v5
	v_mul_f32_e32 v7, v5, v5
	global_store_dwordx2 v8, v[2:3], s[16:17] offset:1536
	v_add_u32_e32 v3, 64, v247
	v_xor_b32_e32 v2, 1, v246
	v_fmac_f32_e32 v7, v4, v4
	v_cmp_lt_i32_e32 vcc, v2, v3
	v_add_f32_e32 v6, v6, v7
	v_add_f32_e32 v6, v9, v6
	v_cndmask_b32_e32 v2, v246, v2, vcc
	v_lshlrev_b32_e32 v2, 2, v2
	ds_bpermute_b32 v2, v2, v6
	v_xor_b32_e32 v4, 2, v246
	v_cmp_lt_i32_e32 vcc, v4, v3
	s_waitcnt lgkmcnt(0)
	v_add_f32_e32 v2, v6, v2
	v_cndmask_b32_e32 v4, v246, v4, vcc
	v_lshlrev_b32_e32 v4, 2, v4
	ds_bpermute_b32 v4, v4, v2
	s_waitcnt lgkmcnt(0)
	v_add_f32_e32 v2, v2, v4
	v_xor_b32_e32 v4, 4, v246
	v_cmp_lt_i32_e32 vcc, v4, v3
	s_nop 1
	v_cndmask_b32_e32 v4, v246, v4, vcc
	v_lshlrev_b32_e32 v4, 2, v4
	ds_bpermute_b32 v4, v4, v2
	s_waitcnt lgkmcnt(0)
	v_add_f32_e32 v2, v2, v4
	v_xor_b32_e32 v4, 8, v246
	v_cmp_lt_i32_e32 vcc, v4, v3
	s_nop 1
	v_cndmask_b32_e32 v4, v246, v4, vcc
	v_lshlrev_b32_e32 v4, 2, v4
	ds_bpermute_b32 v4, v4, v2
	s_waitcnt lgkmcnt(0)
	v_add_f32_e32 v2, v2, v4
	v_xor_b32_e32 v4, 16, v246
	v_cmp_lt_i32_e32 vcc, v4, v3
	s_nop 1
	v_cndmask_b32_e32 v4, v246, v4, vcc
	v_lshlrev_b32_e32 v4, 2, v4
	ds_bpermute_b32 v4, v4, v2
	s_waitcnt lgkmcnt(0)
	v_add_f32_e32 v2, v2, v4
	v_xor_b32_e32 v4, 32, v246
	v_cmp_lt_i32_e32 vcc, v4, v3
	s_nop 1
	v_cndmask_b32_e32 v3, v246, v4, vcc
	v_lshlrev_b32_e32 v3, 2, v3
	ds_bpermute_b32 v3, v3, v2
	s_and_saveexec_b64 s[6:7], s[0:1]
	s_cbranch_execz .LBB0_1211
	s_waitcnt lgkmcnt(0)
	v_add_f32_e32 v2, v2, v3
	global_store_dword v65, v2, s[56:57]
	s_branch .LBB0_1211
